# S5 scan blocks: counted lgkmcnt in front of each pair of k-steps of the f32 MFMA block instead of one full wait after the A-operand reads
# baseline (speedup 1.0000x reference)
; __device__ __forceinline__ int otid() { return otid_full() & 255; }
; __device__ __forceinline__ void s5_pass1(const Params& p, int layer, int task, char* sm) {
;   const int tid = otid(), lane = tid & 63, w = tid >> 6;
;   const int gq = task & 7, c = (task >> 3) & 127, b = task >> 10;
;   const int g = gq * 4 + w;
;   const size_t tok0 = (size_t)b * LSEQ + c * 128;
;   float* sU = (float*)(sm + w * 8192);
;   __syncthreads();
;   s5_load_u(p, tok0 + lane, g, sU + lane * 16);
;   s5_load_u(p, tok0 + 64 + lane, g, sU + (64 + lane) * 16);
;   const size_t pi = ((size_t)(layer * 32 + g)) * 64 + lane;
;   f32x2 B2[16];
; #pragma unroll
;   for (int h = 0; h < 16; h++) { B2[h].x = p.SB[pi * 32 + h]; B2[h].y = p.SB[pi * 32 + 16 + h]; }
;   const float ar = p.SA[pi * 4], ai = p.SA[pi * 4 + 1];
;   float sr = 0.f, si = 0.f;
;   __builtin_amdgcn_wave_barrier();
;   for (int l = 0; l < 128; l++) S5_STEP(sU + l * 16)
.LBB0_477:
	v_mov_b32_e32 v37, v38
	s_nop 1
	v_permlane32_swap_b32_e32 v16, v12
	v_permlane32_swap_b32_e32 v17, v13
	v_permlane32_swap_b32_e32 v18, v14
	v_permlane32_swap_b32_e32 v19, v15
	v_permlane32_swap_b32_e32 v20, v8
	v_permlane32_swap_b32_e32 v21, v9
	v_permlane32_swap_b32_e32 v22, v10
	v_permlane32_swap_b32_e32 v23, v11
	v_permlane32_swap_b32_e32 v24, v4
	v_permlane32_swap_b32_e32 v25, v5
	v_permlane32_swap_b32_e32 v26, v6
	v_permlane32_swap_b32_e32 v27, v7
	v_permlane32_swap_b32_e32 v28, v0
	v_permlane32_swap_b32_e32 v29, v1
	v_permlane32_swap_b32_e32 v30, v2
	v_permlane32_swap_b32_e32 v31, v3
	v_and_b32_e32 v186, 31, v202
	v_lshrrev_b32_e32 v187, 5, v202
	v_lshlrev_b32_e32 v186, 6, v186
	v_lshl_add_u32 v186, v187, 2, v186
	v_add_u32_e32 v186, v41, v186
	ds_read2_b32 v[178:179], v186 offset0:0 offset1:2
	ds_read2_b32 v[180:181], v186 offset0:4 offset1:6
	ds_read2_b32 v[182:183], v186 offset0:8 offset1:10
	ds_read2_b32 v[184:185], v186 offset0:12 offset1:14
	v_add_u32_e32 v186, 0x800, v186
	s_setprio 1
	s_waitcnt lgkmcnt(3)
	v_mfma_f32_32x32x2_f32 v[108:123], v178, v16, 0
	v_mfma_f32_32x32x2_f32 v[124:139], v178, v17, 0
	v_mfma_f32_32x32x2_f32 v[146:161], v178, v12, 0
	v_mfma_f32_32x32x2_f32 v[162:177], v178, v13, 0
	v_mfma_f32_32x32x2_f32 v[108:123], v179, v18, v[108:123]
	v_mfma_f32_32x32x2_f32 v[124:139], v179, v19, v[124:139]
	v_mfma_f32_32x32x2_f32 v[146:161], v179, v14, v[146:161]
	v_mfma_f32_32x32x2_f32 v[162:177], v179, v15, v[162:177]
	s_waitcnt lgkmcnt(2)
	v_mfma_f32_32x32x2_f32 v[108:123], v180, v20, v[108:123]
	v_mfma_f32_32x32x2_f32 v[124:139], v180, v21, v[124:139]
	v_mfma_f32_32x32x2_f32 v[146:161], v180, v8, v[146:161]
	v_mfma_f32_32x32x2_f32 v[162:177], v180, v9, v[162:177]
	v_mfma_f32_32x32x2_f32 v[108:123], v181, v22, v[108:123]
	v_mfma_f32_32x32x2_f32 v[124:139], v181, v23, v[124:139]
	v_mfma_f32_32x32x2_f32 v[146:161], v181, v10, v[146:161]
	v_mfma_f32_32x32x2_f32 v[162:177], v181, v11, v[162:177]
	s_waitcnt lgkmcnt(1)
	v_mfma_f32_32x32x2_f32 v[108:123], v182, v24, v[108:123]
	v_mfma_f32_32x32x2_f32 v[124:139], v182, v25, v[124:139]
	v_mfma_f32_32x32x2_f32 v[146:161], v182, v4, v[146:161]
	v_mfma_f32_32x32x2_f32 v[162:177], v182, v5, v[162:177]
	v_mfma_f32_32x32x2_f32 v[108:123], v183, v26, v[108:123]
	v_mfma_f32_32x32x2_f32 v[124:139], v183, v27, v[124:139]
	v_mfma_f32_32x32x2_f32 v[146:161], v183, v6, v[146:161]
	v_mfma_f32_32x32x2_f32 v[162:177], v183, v7, v[162:177]
	s_waitcnt lgkmcnt(0)
	v_mfma_f32_32x32x2_f32 v[108:123], v184, v28, v[108:123]
	v_mfma_f32_32x32x2_f32 v[124:139], v184, v29, v[124:139]
	v_mfma_f32_32x32x2_f32 v[146:161], v184, v0, v[146:161]
	v_mfma_f32_32x32x2_f32 v[162:177], v184, v1, v[162:177]
	v_mfma_f32_32x32x2_f32 v[108:123], v185, v30, v[108:123]
	v_mfma_f32_32x32x2_f32 v[124:139], v185, v31, v[124:139]
	v_mfma_f32_32x32x2_f32 v[146:161], v185, v2, v[146:161]
	v_mfma_f32_32x32x2_f32 v[162:177], v185, v3, v[162:177]
	s_setprio 0
	s_nop 7
	s_nop 7
	s_nop 7
	v_permlane32_swap_b32_e32 v108, v146
	v_permlane32_swap_b32_e32 v124, v162
	v_permlane32_swap_b32_e32 v109, v147
	v_permlane32_swap_b32_e32 v125, v163
	v_permlane32_swap_b32_e32 v110, v148
	v_permlane32_swap_b32_e32 v126, v164
	v_permlane32_swap_b32_e32 v111, v149
	v_permlane32_swap_b32_e32 v127, v165
	v_permlane32_swap_b32_e32 v112, v150
	v_permlane32_swap_b32_e32 v128, v166
	v_permlane32_swap_b32_e32 v113, v151
	v_permlane32_swap_b32_e32 v129, v167
	v_permlane32_swap_b32_e32 v114, v152
	v_permlane32_swap_b32_e32 v130, v168
	v_permlane32_swap_b32_e32 v115, v153
	v_permlane32_swap_b32_e32 v131, v169
	v_permlane32_swap_b32_e32 v116, v154
	v_permlane32_swap_b32_e32 v132, v170
	v_permlane32_swap_b32_e32 v117, v155
	v_permlane32_swap_b32_e32 v133, v171
	v_permlane32_swap_b32_e32 v118, v156
	v_permlane32_swap_b32_e32 v134, v172
	v_permlane32_swap_b32_e32 v119, v157
	v_permlane32_swap_b32_e32 v135, v173
	v_permlane32_swap_b32_e32 v120, v158
	v_permlane32_swap_b32_e32 v136, v174
	v_permlane32_swap_b32_e32 v121, v159
	v_permlane32_swap_b32_e32 v137, v175
	v_permlane32_swap_b32_e32 v122, v160
	v_permlane32_swap_b32_e32 v138, v176
	v_permlane32_swap_b32_e32 v123, v161
	v_permlane32_swap_b32_e32 v139, v177
	v_mul_f32_e32 v188, v34, v37
	v_mul_f32_e32 v189, v35, v37
	v_fma_f32 v190, v32, v36, -v188
	v_fma_f32 v191, v33, v36, v189
	v_add_f32_e32 v36, v190, v108
	v_add_f32_e32 v37, v191, v124
	v_mul_f32_e32 v188, v34, v37
	v_mul_f32_e32 v189, v35, v37
	v_fma_f32 v190, v32, v36, -v188
	v_fma_f32 v191, v33, v36, v189
	v_add_f32_e32 v36, v190, v109
	v_add_f32_e32 v37, v191, v125
	v_mul_f32_e32 v188, v34, v37
	v_mul_f32_e32 v189, v35, v37
	v_fma_f32 v190, v32, v36, -v188
	v_fma_f32 v191, v33, v36, v189
	v_add_f32_e32 v36, v190, v110
	v_add_f32_e32 v37, v191, v126
	v_mul_f32_e32 v188, v34, v37
	v_mul_f32_e32 v189, v35, v37
	v_fma_f32 v190, v32, v36, -v188
	v_fma_f32 v191, v33, v36, v189
	v_add_f32_e32 v36, v190, v111
	v_add_f32_e32 v37, v191, v127
	v_mul_f32_e32 v188, v34, v37
	v_mul_f32_e32 v189, v35, v37
	v_fma_f32 v190, v32, v36, -v188
	v_fma_f32 v191, v33, v36, v189
	v_add_f32_e32 v36, v190, v146
	v_add_f32_e32 v37, v191, v162
	v_mul_f32_e32 v188, v34, v37
	v_mul_f32_e32 v189, v35, v37
	v_fma_f32 v190, v32, v36, -v188
	v_fma_f32 v191, v33, v36, v189
	v_add_f32_e32 v36, v190, v147
	v_add_f32_e32 v37, v191, v163
	v_mul_f32_e32 v188, v34, v37
	v_mul_f32_e32 v189, v35, v37
	v_fma_f32 v190, v32, v36, -v188
	v_fma_f32 v191, v33, v36, v189
	v_add_f32_e32 v36, v190, v148
	v_add_f32_e32 v37, v191, v164
	v_mul_f32_e32 v188, v34, v37
	v_mul_f32_e32 v189, v35, v37
	v_fma_f32 v190, v32, v36, -v188
	v_fma_f32 v191, v33, v36, v189
	v_add_f32_e32 v36, v190, v149
; __device__ __forceinline__ void s5_pass1(const Params& p, int layer, int task, char* sm) {
;     ...
;   for (int l = 0; l < 128; l++) S5_STEP(sU + l * 16)
	v_add_f32_e32 v37, v191, v165
	v_mul_f32_e32 v188, v34, v37
	v_mul_f32_e32 v189, v35, v37
	v_fma_f32 v190, v32, v36, -v188
	v_fma_f32 v191, v33, v36, v189
	v_add_f32_e32 v36, v190, v112
	v_add_f32_e32 v37, v191, v128
	v_mul_f32_e32 v188, v34, v37
	v_mul_f32_e32 v189, v35, v37
	v_fma_f32 v190, v32, v36, -v188
	v_fma_f32 v191, v33, v36, v189
	v_add_f32_e32 v36, v190, v113
	v_add_f32_e32 v37, v191, v129
	v_mul_f32_e32 v188, v34, v37
	v_mul_f32_e32 v189, v35, v37
	v_fma_f32 v190, v32, v36, -v188
	v_fma_f32 v191, v33, v36, v189
	v_add_f32_e32 v36, v190, v114
	v_add_f32_e32 v37, v191, v130
	v_mul_f32_e32 v188, v34, v37
	v_mul_f32_e32 v189, v35, v37
	v_fma_f32 v190, v32, v36, -v188
	v_fma_f32 v191, v33, v36, v189
	v_add_f32_e32 v36, v190, v115
	v_add_f32_e32 v37, v191, v131
	v_mul_f32_e32 v188, v34, v37
	v_mul_f32_e32 v189, v35, v37
	v_fma_f32 v190, v32, v36, -v188
	v_fma_f32 v191, v33, v36, v189
	v_add_f32_e32 v36, v190, v150
	v_add_f32_e32 v37, v191, v166
	v_mul_f32_e32 v188, v34, v37
	v_mul_f32_e32 v189, v35, v37
	v_fma_f32 v190, v32, v36, -v188
	v_fma_f32 v191, v33, v36, v189
	v_add_f32_e32 v36, v190, v151
	v_add_f32_e32 v37, v191, v167
	v_mul_f32_e32 v188, v34, v37
	v_mul_f32_e32 v189, v35, v37
	v_fma_f32 v190, v32, v36, -v188
	v_fma_f32 v191, v33, v36, v189
	v_add_f32_e32 v36, v190, v152
	v_add_f32_e32 v37, v191, v168
	v_mul_f32_e32 v188, v34, v37
	v_mul_f32_e32 v189, v35, v37
	v_fma_f32 v190, v32, v36, -v188
	v_fma_f32 v191, v33, v36, v189
	v_add_f32_e32 v36, v190, v153
	v_add_f32_e32 v37, v191, v169
	v_mul_f32_e32 v188, v34, v37
	v_mul_f32_e32 v189, v35, v37
	v_fma_f32 v190, v32, v36, -v188
	v_fma_f32 v191, v33, v36, v189
	v_add_f32_e32 v36, v190, v116
	v_add_f32_e32 v37, v191, v132
	v_mul_f32_e32 v188, v34, v37
	v_mul_f32_e32 v189, v35, v37
	v_fma_f32 v190, v32, v36, -v188
	v_fma_f32 v191, v33, v36, v189
	v_add_f32_e32 v36, v190, v117
	v_add_f32_e32 v37, v191, v133
	v_mul_f32_e32 v188, v34, v37
	v_mul_f32_e32 v189, v35, v37
	v_fma_f32 v190, v32, v36, -v188
	v_fma_f32 v191, v33, v36, v189
	v_add_f32_e32 v36, v190, v118
	v_add_f32_e32 v37, v191, v134
	v_mul_f32_e32 v188, v34, v37
	v_mul_f32_e32 v189, v35, v37
	v_fma_f32 v190, v32, v36, -v188
	v_fma_f32 v191, v33, v36, v189
	v_add_f32_e32 v36, v190, v119
	v_add_f32_e32 v37, v191, v135
	v_mul_f32_e32 v188, v34, v37
	v_mul_f32_e32 v189, v35, v37
	v_fma_f32 v190, v32, v36, -v188
	v_fma_f32 v191, v33, v36, v189
	v_add_f32_e32 v36, v190, v154
	v_add_f32_e32 v37, v191, v170
	v_mul_f32_e32 v188, v34, v37
	v_mul_f32_e32 v189, v35, v37
	v_fma_f32 v190, v32, v36, -v188
	v_fma_f32 v191, v33, v36, v189
	v_add_f32_e32 v36, v190, v155
	v_add_f32_e32 v37, v191, v171
	v_mul_f32_e32 v188, v34, v37
	v_mul_f32_e32 v189, v35, v37
	v_fma_f32 v190, v32, v36, -v188
	v_fma_f32 v191, v33, v36, v189
	v_add_f32_e32 v36, v190, v156
	v_add_f32_e32 v37, v191, v172
	v_mul_f32_e32 v188, v34, v37
	v_mul_f32_e32 v189, v35, v37
	v_fma_f32 v190, v32, v36, -v188
	v_fma_f32 v191, v33, v36, v189
	v_add_f32_e32 v36, v190, v157
	v_add_f32_e32 v37, v191, v173
	v_mul_f32_e32 v188, v34, v37
	v_mul_f32_e32 v189, v35, v37
	v_fma_f32 v190, v32, v36, -v188
	v_fma_f32 v191, v33, v36, v189
	v_add_f32_e32 v36, v190, v120
	v_add_f32_e32 v37, v191, v136
	v_mul_f32_e32 v188, v34, v37
	v_mul_f32_e32 v189, v35, v37
	v_fma_f32 v190, v32, v36, -v188
	v_fma_f32 v191, v33, v36, v189
	v_add_f32_e32 v36, v190, v121
	v_add_f32_e32 v37, v191, v137
	v_mul_f32_e32 v188, v34, v37
	v_mul_f32_e32 v189, v35, v37
	v_fma_f32 v190, v32, v36, -v188
	v_fma_f32 v191, v33, v36, v189
	v_add_f32_e32 v36, v190, v122
	v_add_f32_e32 v37, v191, v138
	v_mul_f32_e32 v188, v34, v37
	v_mul_f32_e32 v189, v35, v37
	v_fma_f32 v190, v32, v36, -v188
	v_fma_f32 v191, v33, v36, v189
	v_add_f32_e32 v36, v190, v123
	v_add_f32_e32 v37, v191, v139
	v_mul_f32_e32 v188, v34, v37
	v_mul_f32_e32 v189, v35, v37
	v_fma_f32 v190, v32, v36, -v188
	v_fma_f32 v191, v33, v36, v189
	v_add_f32_e32 v36, v190, v158
	v_add_f32_e32 v37, v191, v174
	v_mul_f32_e32 v188, v34, v37
	v_mul_f32_e32 v189, v35, v37
	v_fma_f32 v190, v32, v36, -v188
	v_fma_f32 v191, v33, v36, v189
	v_add_f32_e32 v36, v190, v159
	v_add_f32_e32 v37, v191, v175
	v_mul_f32_e32 v188, v34, v37
	v_mul_f32_e32 v189, v35, v37
	v_fma_f32 v190, v32, v36, -v188
	v_fma_f32 v191, v33, v36, v189
	v_add_f32_e32 v36, v190, v160
	v_add_f32_e32 v37, v191, v176
	v_mul_f32_e32 v188, v34, v37
	v_mul_f32_e32 v189, v35, v37
	v_fma_f32 v190, v32, v36, -v188
	v_fma_f32 v191, v33, v36, v189
	v_add_f32_e32 v36, v190, v161
	v_add_f32_e32 v37, v191, v177
	ds_read2_b32 v[178:179], v186 offset0:0 offset1:2
	ds_read2_b32 v[180:181], v186 offset0:4 offset1:6
	ds_read2_b32 v[182:183], v186 offset0:8 offset1:10
	ds_read2_b32 v[184:185], v186 offset0:12 offset1:14
	v_add_u32_e32 v186, 0x800, v186
	s_setprio 1
	s_waitcnt lgkmcnt(3)
	v_mfma_f32_32x32x2_f32 v[108:123], v178, v16, 0
	v_mfma_f32_32x32x2_f32 v[124:139], v178, v17, 0
	v_mfma_f32_32x32x2_f32 v[146:161], v178, v12, 0
	v_mfma_f32_32x32x2_f32 v[162:177], v178, v13, 0
	v_mfma_f32_32x32x2_f32 v[108:123], v179, v18, v[108:123]
	v_mfma_f32_32x32x2_f32 v[124:139], v179, v19, v[124:139]
	v_mfma_f32_32x32x2_f32 v[146:161], v179, v14, v[146:161]
	v_mfma_f32_32x32x2_f32 v[162:177], v179, v15, v[162:177]
	s_waitcnt lgkmcnt(2)
	v_mfma_f32_32x32x2_f32 v[108:123], v180, v20, v[108:123]
	v_mfma_f32_32x32x2_f32 v[124:139], v180, v21, v[124:139]
	v_mfma_f32_32x32x2_f32 v[146:161], v180, v8, v[146:161]
	v_mfma_f32_32x32x2_f32 v[162:177], v180, v9, v[162:177]
	v_mfma_f32_32x32x2_f32 v[108:123], v181, v22, v[108:123]
	v_mfma_f32_32x32x2_f32 v[124:139], v181, v23, v[124:139]
	v_mfma_f32_32x32x2_f32 v[146:161], v181, v10, v[146:161]
	v_mfma_f32_32x32x2_f32 v[162:177], v181, v11, v[162:177]
	s_waitcnt lgkmcnt(1)
; __device__ __forceinline__ void s5_pass1(const Params& p, int layer, int task, char* sm) {
;     ...
;   for (int l = 0; l < 128; l++) S5_STEP(sU + l * 16)
	v_mfma_f32_32x32x2_f32 v[108:123], v182, v24, v[108:123]
	v_mfma_f32_32x32x2_f32 v[124:139], v182, v25, v[124:139]
	v_mfma_f32_32x32x2_f32 v[146:161], v182, v4, v[146:161]
	v_mfma_f32_32x32x2_f32 v[162:177], v182, v5, v[162:177]
	v_mfma_f32_32x32x2_f32 v[108:123], v183, v26, v[108:123]
	v_mfma_f32_32x32x2_f32 v[124:139], v183, v27, v[124:139]
	v_mfma_f32_32x32x2_f32 v[146:161], v183, v6, v[146:161]
	v_mfma_f32_32x32x2_f32 v[162:177], v183, v7, v[162:177]
	s_waitcnt lgkmcnt(0)
	v_mfma_f32_32x32x2_f32 v[108:123], v184, v28, v[108:123]
	v_mfma_f32_32x32x2_f32 v[124:139], v184, v29, v[124:139]
	v_mfma_f32_32x32x2_f32 v[146:161], v184, v0, v[146:161]
	v_mfma_f32_32x32x2_f32 v[162:177], v184, v1, v[162:177]
	v_mfma_f32_32x32x2_f32 v[108:123], v185, v30, v[108:123]
	v_mfma_f32_32x32x2_f32 v[124:139], v185, v31, v[124:139]
	v_mfma_f32_32x32x2_f32 v[146:161], v185, v2, v[146:161]
	v_mfma_f32_32x32x2_f32 v[162:177], v185, v3, v[162:177]
	s_setprio 0
	s_nop 7
	s_nop 7
	s_nop 7
	v_permlane32_swap_b32_e32 v108, v146
	v_permlane32_swap_b32_e32 v124, v162
	v_permlane32_swap_b32_e32 v109, v147
	v_permlane32_swap_b32_e32 v125, v163
	v_permlane32_swap_b32_e32 v110, v148
	v_permlane32_swap_b32_e32 v126, v164
	v_permlane32_swap_b32_e32 v111, v149
	v_permlane32_swap_b32_e32 v127, v165
	v_permlane32_swap_b32_e32 v112, v150
	v_permlane32_swap_b32_e32 v128, v166
	v_permlane32_swap_b32_e32 v113, v151
	v_permlane32_swap_b32_e32 v129, v167
	v_permlane32_swap_b32_e32 v114, v152
	v_permlane32_swap_b32_e32 v130, v168
	v_permlane32_swap_b32_e32 v115, v153
	v_permlane32_swap_b32_e32 v131, v169
	v_permlane32_swap_b32_e32 v116, v154
	v_permlane32_swap_b32_e32 v132, v170
	v_permlane32_swap_b32_e32 v117, v155
	v_permlane32_swap_b32_e32 v133, v171
	v_permlane32_swap_b32_e32 v118, v156
	v_permlane32_swap_b32_e32 v134, v172
	v_permlane32_swap_b32_e32 v119, v157
	v_permlane32_swap_b32_e32 v135, v173
	v_permlane32_swap_b32_e32 v120, v158
	v_permlane32_swap_b32_e32 v136, v174
	v_permlane32_swap_b32_e32 v121, v159
	v_permlane32_swap_b32_e32 v137, v175
	v_permlane32_swap_b32_e32 v122, v160
	v_permlane32_swap_b32_e32 v138, v176
	v_permlane32_swap_b32_e32 v123, v161
	v_permlane32_swap_b32_e32 v139, v177
	v_mul_f32_e32 v188, v34, v37
	v_mul_f32_e32 v189, v35, v37
	v_fma_f32 v190, v32, v36, -v188
	v_fma_f32 v191, v33, v36, v189
	v_add_f32_e32 v36, v190, v108
	v_add_f32_e32 v37, v191, v124
	v_mul_f32_e32 v188, v34, v37
	v_mul_f32_e32 v189, v35, v37
	v_fma_f32 v190, v32, v36, -v188
	v_fma_f32 v191, v33, v36, v189
	v_add_f32_e32 v36, v190, v109
	v_add_f32_e32 v37, v191, v125
	v_mul_f32_e32 v188, v34, v37
	v_mul_f32_e32 v189, v35, v37
	v_fma_f32 v190, v32, v36, -v188
	v_fma_f32 v191, v33, v36, v189
	v_add_f32_e32 v36, v190, v110
	v_add_f32_e32 v37, v191, v126
	v_mul_f32_e32 v188, v34, v37
	v_mul_f32_e32 v189, v35, v37
	v_fma_f32 v190, v32, v36, -v188
	v_fma_f32 v191, v33, v36, v189
	v_add_f32_e32 v36, v190, v111
	v_add_f32_e32 v37, v191, v127
	v_mul_f32_e32 v188, v34, v37
	v_mul_f32_e32 v189, v35, v37
	v_fma_f32 v190, v32, v36, -v188
	v_fma_f32 v191, v33, v36, v189
	v_add_f32_e32 v36, v190, v146
	v_add_f32_e32 v37, v191, v162
	v_mul_f32_e32 v188, v34, v37
	v_mul_f32_e32 v189, v35, v37
	v_fma_f32 v190, v32, v36, -v188
	v_fma_f32 v191, v33, v36, v189
	v_add_f32_e32 v36, v190, v147
	v_add_f32_e32 v37, v191, v163
	v_mul_f32_e32 v188, v34, v37
	v_mul_f32_e32 v189, v35, v37
	v_fma_f32 v190, v32, v36, -v188
	v_fma_f32 v191, v33, v36, v189
	v_add_f32_e32 v36, v190, v148
	v_add_f32_e32 v37, v191, v164
	v_mul_f32_e32 v188, v34, v37
	v_mul_f32_e32 v189, v35, v37
	v_fma_f32 v190, v32, v36, -v188
	v_fma_f32 v191, v33, v36, v189
	v_add_f32_e32 v36, v190, v149
	v_add_f32_e32 v37, v191, v165
	v_mul_f32_e32 v188, v34, v37
	v_mul_f32_e32 v189, v35, v37
	v_fma_f32 v190, v32, v36, -v188
	v_fma_f32 v191, v33, v36, v189
	v_add_f32_e32 v36, v190, v112
	v_add_f32_e32 v37, v191, v128
	v_mul_f32_e32 v188, v34, v37
	v_mul_f32_e32 v189, v35, v37
	v_fma_f32 v190, v32, v36, -v188
	v_fma_f32 v191, v33, v36, v189
	v_add_f32_e32 v36, v190, v113
	v_add_f32_e32 v37, v191, v129
	v_mul_f32_e32 v188, v34, v37
	v_mul_f32_e32 v189, v35, v37
	v_fma_f32 v190, v32, v36, -v188
	v_fma_f32 v191, v33, v36, v189
	v_add_f32_e32 v36, v190, v114
	v_add_f32_e32 v37, v191, v130
	v_mul_f32_e32 v188, v34, v37
	v_mul_f32_e32 v189, v35, v37
	v_fma_f32 v190, v32, v36, -v188
	v_fma_f32 v191, v33, v36, v189
	v_add_f32_e32 v36, v190, v115
	v_add_f32_e32 v37, v191, v131
	v_mul_f32_e32 v188, v34, v37
	v_mul_f32_e32 v189, v35, v37
	v_fma_f32 v190, v32, v36, -v188
	v_fma_f32 v191, v33, v36, v189
	v_add_f32_e32 v36, v190, v150
	v_add_f32_e32 v37, v191, v166
	v_mul_f32_e32 v188, v34, v37
	v_mul_f32_e32 v189, v35, v37
	v_fma_f32 v190, v32, v36, -v188
	v_fma_f32 v191, v33, v36, v189
	v_add_f32_e32 v36, v190, v151
	v_add_f32_e32 v37, v191, v167
	v_mul_f32_e32 v188, v34, v37
	v_mul_f32_e32 v189, v35, v37
	v_fma_f32 v190, v32, v36, -v188
	v_fma_f32 v191, v33, v36, v189
	v_add_f32_e32 v36, v190, v152
	v_add_f32_e32 v37, v191, v168
	v_mul_f32_e32 v188, v34, v37
	v_mul_f32_e32 v189, v35, v37
	v_fma_f32 v190, v32, v36, -v188
	v_fma_f32 v191, v33, v36, v189
	v_add_f32_e32 v36, v190, v153
	v_add_f32_e32 v37, v191, v169
	v_mul_f32_e32 v188, v34, v37
	v_mul_f32_e32 v189, v35, v37
	v_fma_f32 v190, v32, v36, -v188
	v_fma_f32 v191, v33, v36, v189
	v_add_f32_e32 v36, v190, v116
	v_add_f32_e32 v37, v191, v132
	v_mul_f32_e32 v188, v34, v37
	v_mul_f32_e32 v189, v35, v37
	v_fma_f32 v190, v32, v36, -v188
	v_fma_f32 v191, v33, v36, v189
	v_add_f32_e32 v36, v190, v117
	v_add_f32_e32 v37, v191, v133
	v_mul_f32_e32 v188, v34, v37
	v_mul_f32_e32 v189, v35, v37
; __device__ __forceinline__ void s5_pass1(const Params& p, int layer, int task, char* sm) {
;     ...
;   for (int l = 0; l < 128; l++) S5_STEP(sU + l * 16)
	v_fma_f32 v190, v32, v36, -v188
	v_fma_f32 v191, v33, v36, v189
	v_add_f32_e32 v36, v190, v118
	v_add_f32_e32 v37, v191, v134
	v_mul_f32_e32 v188, v34, v37
	v_mul_f32_e32 v189, v35, v37
	v_fma_f32 v190, v32, v36, -v188
	v_fma_f32 v191, v33, v36, v189
	v_add_f32_e32 v36, v190, v119
	v_add_f32_e32 v37, v191, v135
	v_mul_f32_e32 v188, v34, v37
	v_mul_f32_e32 v189, v35, v37
	v_fma_f32 v190, v32, v36, -v188
	v_fma_f32 v191, v33, v36, v189
	v_add_f32_e32 v36, v190, v154
	v_add_f32_e32 v37, v191, v170
	v_mul_f32_e32 v188, v34, v37
	v_mul_f32_e32 v189, v35, v37
	v_fma_f32 v190, v32, v36, -v188
	v_fma_f32 v191, v33, v36, v189
	v_add_f32_e32 v36, v190, v155
	v_add_f32_e32 v37, v191, v171
	v_mul_f32_e32 v188, v34, v37
	v_mul_f32_e32 v189, v35, v37
	v_fma_f32 v190, v32, v36, -v188
	v_fma_f32 v191, v33, v36, v189
	v_add_f32_e32 v36, v190, v156
	v_add_f32_e32 v37, v191, v172
	v_mul_f32_e32 v188, v34, v37
	v_mul_f32_e32 v189, v35, v37
	v_fma_f32 v190, v32, v36, -v188
	v_fma_f32 v191, v33, v36, v189
	v_add_f32_e32 v36, v190, v157
	v_add_f32_e32 v37, v191, v173
	v_mul_f32_e32 v188, v34, v37
	v_mul_f32_e32 v189, v35, v37
	v_fma_f32 v190, v32, v36, -v188
	v_fma_f32 v191, v33, v36, v189
	v_add_f32_e32 v36, v190, v120
	v_add_f32_e32 v37, v191, v136
	v_mul_f32_e32 v188, v34, v37
	v_mul_f32_e32 v189, v35, v37
	v_fma_f32 v190, v32, v36, -v188
	v_fma_f32 v191, v33, v36, v189
	v_add_f32_e32 v36, v190, v121
	v_add_f32_e32 v37, v191, v137
	v_mul_f32_e32 v188, v34, v37
	v_mul_f32_e32 v189, v35, v37
	v_fma_f32 v190, v32, v36, -v188
	v_fma_f32 v191, v33, v36, v189
	v_add_f32_e32 v36, v190, v122
	v_add_f32_e32 v37, v191, v138
	v_mul_f32_e32 v188, v34, v37
	v_mul_f32_e32 v189, v35, v37
	v_fma_f32 v190, v32, v36, -v188
	v_fma_f32 v191, v33, v36, v189
	v_add_f32_e32 v36, v190, v123
	v_add_f32_e32 v37, v191, v139
	v_mul_f32_e32 v188, v34, v37
	v_mul_f32_e32 v189, v35, v37
	v_fma_f32 v190, v32, v36, -v188
	v_fma_f32 v191, v33, v36, v189
	v_add_f32_e32 v36, v190, v158
	v_add_f32_e32 v37, v191, v174
	v_mul_f32_e32 v188, v34, v37
	v_mul_f32_e32 v189, v35, v37
	v_fma_f32 v190, v32, v36, -v188
	v_fma_f32 v191, v33, v36, v189
	v_add_f32_e32 v36, v190, v159
	v_add_f32_e32 v37, v191, v175
	v_mul_f32_e32 v188, v34, v37
	v_mul_f32_e32 v189, v35, v37
	v_fma_f32 v190, v32, v36, -v188
	v_fma_f32 v191, v33, v36, v189
	v_add_f32_e32 v36, v190, v160
	v_add_f32_e32 v37, v191, v176
	v_mul_f32_e32 v188, v34, v37
	v_mul_f32_e32 v189, v35, v37
	v_fma_f32 v190, v32, v36, -v188
	v_fma_f32 v191, v33, v36, v189
	v_add_f32_e32 v36, v190, v161
	v_add_f32_e32 v37, v191, v177
	ds_read2_b32 v[178:179], v186 offset0:0 offset1:2
	ds_read2_b32 v[180:181], v186 offset0:4 offset1:6
	ds_read2_b32 v[182:183], v186 offset0:8 offset1:10
	ds_read2_b32 v[184:185], v186 offset0:12 offset1:14
	v_add_u32_e32 v186, 0x800, v186
	s_setprio 1
	s_waitcnt lgkmcnt(3)
	v_mfma_f32_32x32x2_f32 v[108:123], v178, v16, 0
	v_mfma_f32_32x32x2_f32 v[124:139], v178, v17, 0
	v_mfma_f32_32x32x2_f32 v[146:161], v178, v12, 0
	v_mfma_f32_32x32x2_f32 v[162:177], v178, v13, 0
	v_mfma_f32_32x32x2_f32 v[108:123], v179, v18, v[108:123]
	v_mfma_f32_32x32x2_f32 v[124:139], v179, v19, v[124:139]
	v_mfma_f32_32x32x2_f32 v[146:161], v179, v14, v[146:161]
	v_mfma_f32_32x32x2_f32 v[162:177], v179, v15, v[162:177]
	s_waitcnt lgkmcnt(2)
	v_mfma_f32_32x32x2_f32 v[108:123], v180, v20, v[108:123]
	v_mfma_f32_32x32x2_f32 v[124:139], v180, v21, v[124:139]
	v_mfma_f32_32x32x2_f32 v[146:161], v180, v8, v[146:161]
	v_mfma_f32_32x32x2_f32 v[162:177], v180, v9, v[162:177]
	v_mfma_f32_32x32x2_f32 v[108:123], v181, v22, v[108:123]
	v_mfma_f32_32x32x2_f32 v[124:139], v181, v23, v[124:139]
	v_mfma_f32_32x32x2_f32 v[146:161], v181, v10, v[146:161]
	v_mfma_f32_32x32x2_f32 v[162:177], v181, v11, v[162:177]
	s_waitcnt lgkmcnt(1)
	v_mfma_f32_32x32x2_f32 v[108:123], v182, v24, v[108:123]
	v_mfma_f32_32x32x2_f32 v[124:139], v182, v25, v[124:139]
	v_mfma_f32_32x32x2_f32 v[146:161], v182, v4, v[146:161]
	v_mfma_f32_32x32x2_f32 v[162:177], v182, v5, v[162:177]
	v_mfma_f32_32x32x2_f32 v[108:123], v183, v26, v[108:123]
	v_mfma_f32_32x32x2_f32 v[124:139], v183, v27, v[124:139]
	v_mfma_f32_32x32x2_f32 v[146:161], v183, v6, v[146:161]
	v_mfma_f32_32x32x2_f32 v[162:177], v183, v7, v[162:177]
	s_waitcnt lgkmcnt(0)
; __device__ __forceinline__ void s5_pass1(const Params& p, int layer, int task, char* sm) {
;     ...
;   for (int l = 0; l < 128; l++) S5_STEP(sU + l * 16)
	v_mfma_f32_32x32x2_f32 v[108:123], v184, v28, v[108:123]
	v_mfma_f32_32x32x2_f32 v[124:139], v184, v29, v[124:139]
	v_mfma_f32_32x32x2_f32 v[146:161], v184, v0, v[146:161]
	v_mfma_f32_32x32x2_f32 v[162:177], v184, v1, v[162:177]
	v_mfma_f32_32x32x2_f32 v[108:123], v185, v30, v[108:123]
	v_mfma_f32_32x32x2_f32 v[124:139], v185, v31, v[124:139]
	v_mfma_f32_32x32x2_f32 v[146:161], v185, v2, v[146:161]
	v_mfma_f32_32x32x2_f32 v[162:177], v185, v3, v[162:177]
	s_setprio 0
	s_nop 7
	s_nop 7
	s_nop 7
	v_permlane32_swap_b32_e32 v108, v146
	v_permlane32_swap_b32_e32 v124, v162
	v_permlane32_swap_b32_e32 v109, v147
	v_permlane32_swap_b32_e32 v125, v163
	v_permlane32_swap_b32_e32 v110, v148
	v_permlane32_swap_b32_e32 v126, v164
	v_permlane32_swap_b32_e32 v111, v149
	v_permlane32_swap_b32_e32 v127, v165
	v_permlane32_swap_b32_e32 v112, v150
	v_permlane32_swap_b32_e32 v128, v166
	v_permlane32_swap_b32_e32 v113, v151
	v_permlane32_swap_b32_e32 v129, v167
	v_permlane32_swap_b32_e32 v114, v152
	v_permlane32_swap_b32_e32 v130, v168
	v_permlane32_swap_b32_e32 v115, v153
	v_permlane32_swap_b32_e32 v131, v169
	v_permlane32_swap_b32_e32 v116, v154
	v_permlane32_swap_b32_e32 v132, v170
	v_permlane32_swap_b32_e32 v117, v155
	v_permlane32_swap_b32_e32 v133, v171
	v_permlane32_swap_b32_e32 v118, v156
	v_permlane32_swap_b32_e32 v134, v172
	v_permlane32_swap_b32_e32 v119, v157
	v_permlane32_swap_b32_e32 v135, v173
	v_permlane32_swap_b32_e32 v120, v158
	v_permlane32_swap_b32_e32 v136, v174
	v_permlane32_swap_b32_e32 v121, v159
	v_permlane32_swap_b32_e32 v137, v175
	v_permlane32_swap_b32_e32 v122, v160
	v_permlane32_swap_b32_e32 v138, v176
	v_permlane32_swap_b32_e32 v123, v161
	v_permlane32_swap_b32_e32 v139, v177
	v_mul_f32_e32 v188, v34, v37
	v_mul_f32_e32 v189, v35, v37
	v_fma_f32 v190, v32, v36, -v188
	v_fma_f32 v191, v33, v36, v189
	v_add_f32_e32 v36, v190, v108
	v_add_f32_e32 v37, v191, v124
	v_mul_f32_e32 v188, v34, v37
	v_mul_f32_e32 v189, v35, v37
	v_fma_f32 v190, v32, v36, -v188
	v_fma_f32 v191, v33, v36, v189
	v_add_f32_e32 v36, v190, v109
	v_add_f32_e32 v37, v191, v125
	v_mul_f32_e32 v188, v34, v37
	v_mul_f32_e32 v189, v35, v37
	v_fma_f32 v190, v32, v36, -v188
	v_fma_f32 v191, v33, v36, v189
	v_add_f32_e32 v36, v190, v110
	v_add_f32_e32 v37, v191, v126
	v_mul_f32_e32 v188, v34, v37
	v_mul_f32_e32 v189, v35, v37
	v_fma_f32 v190, v32, v36, -v188
	v_fma_f32 v191, v33, v36, v189
	v_add_f32_e32 v36, v190, v111
	v_add_f32_e32 v37, v191, v127
	v_mul_f32_e32 v188, v34, v37
	v_mul_f32_e32 v189, v35, v37
	v_fma_f32 v190, v32, v36, -v188
	v_fma_f32 v191, v33, v36, v189
	v_add_f32_e32 v36, v190, v146
	v_add_f32_e32 v37, v191, v162
	v_mul_f32_e32 v188, v34, v37
	v_mul_f32_e32 v189, v35, v37
	v_fma_f32 v190, v32, v36, -v188
	v_fma_f32 v191, v33, v36, v189
	v_add_f32_e32 v36, v190, v147
	v_add_f32_e32 v37, v191, v163
	v_mul_f32_e32 v188, v34, v37
	v_mul_f32_e32 v189, v35, v37
	v_fma_f32 v190, v32, v36, -v188
	v_fma_f32 v191, v33, v36, v189
	v_add_f32_e32 v36, v190, v148
	v_add_f32_e32 v37, v191, v164
	v_mul_f32_e32 v188, v34, v37
	v_mul_f32_e32 v189, v35, v37
	v_fma_f32 v190, v32, v36, -v188
	v_fma_f32 v191, v33, v36, v189
	v_add_f32_e32 v36, v190, v149
	v_add_f32_e32 v37, v191, v165
	v_mul_f32_e32 v188, v34, v37
	v_mul_f32_e32 v189, v35, v37
	v_fma_f32 v190, v32, v36, -v188
	v_fma_f32 v191, v33, v36, v189
	v_add_f32_e32 v36, v190, v112
	v_add_f32_e32 v37, v191, v128
	v_mul_f32_e32 v188, v34, v37
	v_mul_f32_e32 v189, v35, v37
	v_fma_f32 v190, v32, v36, -v188
	v_fma_f32 v191, v33, v36, v189
	v_add_f32_e32 v36, v190, v113
	v_add_f32_e32 v37, v191, v129
	v_mul_f32_e32 v188, v34, v37
	v_mul_f32_e32 v189, v35, v37
	v_fma_f32 v190, v32, v36, -v188
	v_fma_f32 v191, v33, v36, v189
	v_add_f32_e32 v36, v190, v114
	v_add_f32_e32 v37, v191, v130
	v_mul_f32_e32 v188, v34, v37
	v_mul_f32_e32 v189, v35, v37
	v_fma_f32 v190, v32, v36, -v188
	v_fma_f32 v191, v33, v36, v189
	v_add_f32_e32 v36, v190, v115
	v_add_f32_e32 v37, v191, v131
	v_mul_f32_e32 v188, v34, v37
	v_mul_f32_e32 v189, v35, v37
	v_fma_f32 v190, v32, v36, -v188
	v_fma_f32 v191, v33, v36, v189
	v_add_f32_e32 v36, v190, v150
	v_add_f32_e32 v37, v191, v166
	v_mul_f32_e32 v188, v34, v37
	v_mul_f32_e32 v189, v35, v37
	v_fma_f32 v190, v32, v36, -v188
	v_fma_f32 v191, v33, v36, v189
	v_add_f32_e32 v36, v190, v151
	v_add_f32_e32 v37, v191, v167
	v_mul_f32_e32 v188, v34, v37
	v_mul_f32_e32 v189, v35, v37
	v_fma_f32 v190, v32, v36, -v188
	v_fma_f32 v191, v33, v36, v189
	v_add_f32_e32 v36, v190, v152
	v_add_f32_e32 v37, v191, v168
	v_mul_f32_e32 v188, v34, v37
	v_mul_f32_e32 v189, v35, v37
	v_fma_f32 v190, v32, v36, -v188
	v_fma_f32 v191, v33, v36, v189
	v_add_f32_e32 v36, v190, v153
	v_add_f32_e32 v37, v191, v169
	v_mul_f32_e32 v188, v34, v37
	v_mul_f32_e32 v189, v35, v37
	v_fma_f32 v190, v32, v36, -v188
	v_fma_f32 v191, v33, v36, v189
	v_add_f32_e32 v36, v190, v116
	v_add_f32_e32 v37, v191, v132
	v_mul_f32_e32 v188, v34, v37
	v_mul_f32_e32 v189, v35, v37
	v_fma_f32 v190, v32, v36, -v188
	v_fma_f32 v191, v33, v36, v189
	v_add_f32_e32 v36, v190, v117
	v_add_f32_e32 v37, v191, v133
	v_mul_f32_e32 v188, v34, v37
	v_mul_f32_e32 v189, v35, v37
	v_fma_f32 v190, v32, v36, -v188
	v_fma_f32 v191, v33, v36, v189
	v_add_f32_e32 v36, v190, v118
	v_add_f32_e32 v37, v191, v134
	v_mul_f32_e32 v188, v34, v37
	v_mul_f32_e32 v189, v35, v37
	v_fma_f32 v190, v32, v36, -v188
	v_fma_f32 v191, v33, v36, v189
	v_add_f32_e32 v36, v190, v119
	v_add_f32_e32 v37, v191, v135
	v_mul_f32_e32 v188, v34, v37
	v_mul_f32_e32 v189, v35, v37
	v_fma_f32 v190, v32, v36, -v188
	v_fma_f32 v191, v33, v36, v189
	v_add_f32_e32 v36, v190, v154
	v_add_f32_e32 v37, v191, v170
; __device__ __forceinline__ void s5_pass1(const Params& p, int layer, int task, char* sm) {
;     ...
;   for (int l = 0; l < 128; l++) S5_STEP(sU + l * 16)
	v_mul_f32_e32 v188, v34, v37
	v_mul_f32_e32 v189, v35, v37
	v_fma_f32 v190, v32, v36, -v188
	v_fma_f32 v191, v33, v36, v189
	v_add_f32_e32 v36, v190, v155
	v_add_f32_e32 v37, v191, v171
	v_mul_f32_e32 v188, v34, v37
	v_mul_f32_e32 v189, v35, v37
	v_fma_f32 v190, v32, v36, -v188
	v_fma_f32 v191, v33, v36, v189
	v_add_f32_e32 v36, v190, v156
	v_add_f32_e32 v37, v191, v172
	v_mul_f32_e32 v188, v34, v37
	v_mul_f32_e32 v189, v35, v37
	v_fma_f32 v190, v32, v36, -v188
	v_fma_f32 v191, v33, v36, v189
	v_add_f32_e32 v36, v190, v157
	v_add_f32_e32 v37, v191, v173
	v_mul_f32_e32 v188, v34, v37
	v_mul_f32_e32 v189, v35, v37
	v_fma_f32 v190, v32, v36, -v188
	v_fma_f32 v191, v33, v36, v189
	v_add_f32_e32 v36, v190, v120
	v_add_f32_e32 v37, v191, v136
	v_mul_f32_e32 v188, v34, v37
	v_mul_f32_e32 v189, v35, v37
	v_fma_f32 v190, v32, v36, -v188
	v_fma_f32 v191, v33, v36, v189
	v_add_f32_e32 v36, v190, v121
	v_add_f32_e32 v37, v191, v137
	v_mul_f32_e32 v188, v34, v37
	v_mul_f32_e32 v189, v35, v37
	v_fma_f32 v190, v32, v36, -v188
	v_fma_f32 v191, v33, v36, v189
	v_add_f32_e32 v36, v190, v122
	v_add_f32_e32 v37, v191, v138
	v_mul_f32_e32 v188, v34, v37
	v_mul_f32_e32 v189, v35, v37
	v_fma_f32 v190, v32, v36, -v188
	v_fma_f32 v191, v33, v36, v189
	v_add_f32_e32 v36, v190, v123
	v_add_f32_e32 v37, v191, v139
	v_mul_f32_e32 v188, v34, v37
	v_mul_f32_e32 v189, v35, v37
	v_fma_f32 v190, v32, v36, -v188
	v_fma_f32 v191, v33, v36, v189
	v_add_f32_e32 v36, v190, v158
	v_add_f32_e32 v37, v191, v174
	v_mul_f32_e32 v188, v34, v37
	v_mul_f32_e32 v189, v35, v37
	v_fma_f32 v190, v32, v36, -v188
	v_fma_f32 v191, v33, v36, v189
	v_add_f32_e32 v36, v190, v159
	v_add_f32_e32 v37, v191, v175
	v_mul_f32_e32 v188, v34, v37
	v_mul_f32_e32 v189, v35, v37
	v_fma_f32 v190, v32, v36, -v188
	v_fma_f32 v191, v33, v36, v189
	v_add_f32_e32 v36, v190, v160
	v_add_f32_e32 v37, v191, v176
	v_mul_f32_e32 v188, v34, v37
	v_mul_f32_e32 v189, v35, v37
	v_fma_f32 v190, v32, v36, -v188
	v_fma_f32 v191, v33, v36, v189
	v_add_f32_e32 v36, v190, v161
	v_add_f32_e32 v37, v191, v177
	ds_read2_b32 v[178:179], v186 offset0:0 offset1:2
	ds_read2_b32 v[180:181], v186 offset0:4 offset1:6
	ds_read2_b32 v[182:183], v186 offset0:8 offset1:10
	ds_read2_b32 v[184:185], v186 offset0:12 offset1:14
	s_setprio 1
	s_waitcnt lgkmcnt(3)
	v_mfma_f32_32x32x2_f32 v[108:123], v178, v16, 0
	v_mfma_f32_32x32x2_f32 v[124:139], v178, v17, 0
	v_mfma_f32_32x32x2_f32 v[146:161], v178, v12, 0
	v_mfma_f32_32x32x2_f32 v[162:177], v178, v13, 0
	v_mfma_f32_32x32x2_f32 v[108:123], v179, v18, v[108:123]
	v_mfma_f32_32x32x2_f32 v[124:139], v179, v19, v[124:139]
	v_mfma_f32_32x32x2_f32 v[146:161], v179, v14, v[146:161]
	v_mfma_f32_32x32x2_f32 v[162:177], v179, v15, v[162:177]
	s_waitcnt lgkmcnt(2)
	v_mfma_f32_32x32x2_f32 v[108:123], v180, v20, v[108:123]
	v_mfma_f32_32x32x2_f32 v[124:139], v180, v21, v[124:139]
	v_mfma_f32_32x32x2_f32 v[146:161], v180, v8, v[146:161]
	v_mfma_f32_32x32x2_f32 v[162:177], v180, v9, v[162:177]
	v_mfma_f32_32x32x2_f32 v[108:123], v181, v22, v[108:123]
	v_mfma_f32_32x32x2_f32 v[124:139], v181, v23, v[124:139]
	v_mfma_f32_32x32x2_f32 v[146:161], v181, v10, v[146:161]
	v_mfma_f32_32x32x2_f32 v[162:177], v181, v11, v[162:177]
	s_waitcnt lgkmcnt(1)
	v_mfma_f32_32x32x2_f32 v[108:123], v182, v24, v[108:123]
	v_mfma_f32_32x32x2_f32 v[124:139], v182, v25, v[124:139]
	v_mfma_f32_32x32x2_f32 v[146:161], v182, v4, v[146:161]
	v_mfma_f32_32x32x2_f32 v[162:177], v182, v5, v[162:177]
	v_mfma_f32_32x32x2_f32 v[108:123], v183, v26, v[108:123]
	v_mfma_f32_32x32x2_f32 v[124:139], v183, v27, v[124:139]
	v_mfma_f32_32x32x2_f32 v[146:161], v183, v6, v[146:161]
	v_mfma_f32_32x32x2_f32 v[162:177], v183, v7, v[162:177]
	s_waitcnt lgkmcnt(0)
	v_mfma_f32_32x32x2_f32 v[108:123], v184, v28, v[108:123]
	v_mfma_f32_32x32x2_f32 v[124:139], v184, v29, v[124:139]
	v_mfma_f32_32x32x2_f32 v[146:161], v184, v0, v[146:161]
	v_mfma_f32_32x32x2_f32 v[162:177], v184, v1, v[162:177]
	v_mfma_f32_32x32x2_f32 v[108:123], v185, v30, v[108:123]
	v_mfma_f32_32x32x2_f32 v[124:139], v185, v31, v[124:139]
	v_mfma_f32_32x32x2_f32 v[146:161], v185, v2, v[146:161]
	v_mfma_f32_32x32x2_f32 v[162:177], v185, v3, v[162:177]
	s_setprio 0
	s_nop 7
	s_nop 7
	s_nop 7
	v_permlane32_swap_b32_e32 v108, v146
	v_permlane32_swap_b32_e32 v124, v162
	v_permlane32_swap_b32_e32 v109, v147
	v_permlane32_swap_b32_e32 v125, v163
	v_permlane32_swap_b32_e32 v110, v148
	v_permlane32_swap_b32_e32 v126, v164
	v_permlane32_swap_b32_e32 v111, v149
	v_permlane32_swap_b32_e32 v127, v165
	v_permlane32_swap_b32_e32 v112, v150
	v_permlane32_swap_b32_e32 v128, v166
	v_permlane32_swap_b32_e32 v113, v151
	v_permlane32_swap_b32_e32 v129, v167
	v_permlane32_swap_b32_e32 v114, v152
	v_permlane32_swap_b32_e32 v130, v168
	v_permlane32_swap_b32_e32 v115, v153
	v_permlane32_swap_b32_e32 v131, v169
	v_permlane32_swap_b32_e32 v116, v154
	v_permlane32_swap_b32_e32 v132, v170
	v_permlane32_swap_b32_e32 v117, v155
	v_permlane32_swap_b32_e32 v133, v171
	v_permlane32_swap_b32_e32 v118, v156
	v_permlane32_swap_b32_e32 v134, v172
	v_permlane32_swap_b32_e32 v119, v157
	v_permlane32_swap_b32_e32 v135, v173
	v_permlane32_swap_b32_e32 v120, v158
	v_permlane32_swap_b32_e32 v136, v174
	v_permlane32_swap_b32_e32 v121, v159
	v_permlane32_swap_b32_e32 v137, v175
	v_permlane32_swap_b32_e32 v122, v160
	v_permlane32_swap_b32_e32 v138, v176
	v_permlane32_swap_b32_e32 v123, v161
	v_permlane32_swap_b32_e32 v139, v177
	v_mul_f32_e32 v188, v34, v37
	v_mul_f32_e32 v189, v35, v37
	v_fma_f32 v190, v32, v36, -v188
	v_fma_f32 v191, v33, v36, v189
	v_add_f32_e32 v36, v190, v108
	v_add_f32_e32 v37, v191, v124
	v_mul_f32_e32 v188, v34, v37
; __device__ __forceinline__ void s5_pass1(const Params& p, int layer, int task, char* sm) {
;     ...
;   for (int l = 0; l < 128; l++) S5_STEP(sU + l * 16)
;   *(float2*)(p.END + (((size_t)(b * 128 + c) * 32 + g) * 64 + lane) * 2) = make_float2(sr, si);
	v_mul_f32_e32 v189, v35, v37
	v_fma_f32 v190, v32, v36, -v188
	v_fma_f32 v191, v33, v36, v189
	v_add_f32_e32 v36, v190, v109
	v_add_f32_e32 v37, v191, v125
	v_mul_f32_e32 v188, v34, v37
	v_mul_f32_e32 v189, v35, v37
	v_fma_f32 v190, v32, v36, -v188
	v_fma_f32 v191, v33, v36, v189
	v_add_f32_e32 v36, v190, v110
	v_add_f32_e32 v37, v191, v126
	v_mul_f32_e32 v188, v34, v37
	v_mul_f32_e32 v189, v35, v37
	v_fma_f32 v190, v32, v36, -v188
	v_fma_f32 v191, v33, v36, v189
	v_add_f32_e32 v36, v190, v111
	v_add_f32_e32 v37, v191, v127
	v_mul_f32_e32 v188, v34, v37
	v_mul_f32_e32 v189, v35, v37
	v_fma_f32 v190, v32, v36, -v188
	v_fma_f32 v191, v33, v36, v189
	v_add_f32_e32 v36, v190, v146
	v_add_f32_e32 v37, v191, v162
	v_mul_f32_e32 v188, v34, v37
	v_mul_f32_e32 v189, v35, v37
	v_fma_f32 v190, v32, v36, -v188
	v_fma_f32 v191, v33, v36, v189
	v_add_f32_e32 v36, v190, v147
	v_add_f32_e32 v37, v191, v163
	v_mul_f32_e32 v188, v34, v37
	v_mul_f32_e32 v189, v35, v37
	v_fma_f32 v190, v32, v36, -v188
	v_fma_f32 v191, v33, v36, v189
	v_add_f32_e32 v36, v190, v148
	v_add_f32_e32 v37, v191, v164
	v_mul_f32_e32 v188, v34, v37
	v_mul_f32_e32 v189, v35, v37
	v_fma_f32 v190, v32, v36, -v188
	v_fma_f32 v191, v33, v36, v189
	v_add_f32_e32 v36, v190, v149
	v_add_f32_e32 v37, v191, v165
	v_mul_f32_e32 v188, v34, v37
	v_mul_f32_e32 v189, v35, v37
	v_fma_f32 v190, v32, v36, -v188
	v_fma_f32 v191, v33, v36, v189
	v_add_f32_e32 v36, v190, v112
	v_add_f32_e32 v37, v191, v128
	v_mul_f32_e32 v188, v34, v37
	v_mul_f32_e32 v189, v35, v37
	v_fma_f32 v190, v32, v36, -v188
	v_fma_f32 v191, v33, v36, v189
	v_add_f32_e32 v36, v190, v113
	v_add_f32_e32 v37, v191, v129
	v_mul_f32_e32 v188, v34, v37
	v_mul_f32_e32 v189, v35, v37
	v_fma_f32 v190, v32, v36, -v188
	v_fma_f32 v191, v33, v36, v189
	v_add_f32_e32 v36, v190, v114
	v_add_f32_e32 v37, v191, v130
	v_mul_f32_e32 v188, v34, v37
	v_mul_f32_e32 v189, v35, v37
	v_fma_f32 v190, v32, v36, -v188
	v_fma_f32 v191, v33, v36, v189
	v_add_f32_e32 v36, v190, v115
	v_add_f32_e32 v37, v191, v131
	v_mul_f32_e32 v188, v34, v37
	v_mul_f32_e32 v189, v35, v37
	v_fma_f32 v190, v32, v36, -v188
	v_fma_f32 v191, v33, v36, v189
	v_add_f32_e32 v36, v190, v150
	v_add_f32_e32 v37, v191, v166
	v_mul_f32_e32 v188, v34, v37
	v_mul_f32_e32 v189, v35, v37
	v_fma_f32 v190, v32, v36, -v188
	v_fma_f32 v191, v33, v36, v189
	v_add_f32_e32 v36, v190, v151
	v_add_f32_e32 v37, v191, v167
	v_mul_f32_e32 v188, v34, v37
	v_mul_f32_e32 v189, v35, v37
	v_fma_f32 v190, v32, v36, -v188
	v_fma_f32 v191, v33, v36, v189
	v_add_f32_e32 v36, v190, v152
	v_add_f32_e32 v37, v191, v168
	v_mul_f32_e32 v188, v34, v37
	v_mul_f32_e32 v189, v35, v37
	v_fma_f32 v190, v32, v36, -v188
	v_fma_f32 v191, v33, v36, v189
	v_add_f32_e32 v36, v190, v153
	v_add_f32_e32 v37, v191, v169
	v_mul_f32_e32 v188, v34, v37
	v_mul_f32_e32 v189, v35, v37
	v_fma_f32 v190, v32, v36, -v188
	v_fma_f32 v191, v33, v36, v189
	v_add_f32_e32 v36, v190, v116
	v_add_f32_e32 v37, v191, v132
	v_mul_f32_e32 v188, v34, v37
	v_mul_f32_e32 v189, v35, v37
	v_fma_f32 v190, v32, v36, -v188
	v_fma_f32 v191, v33, v36, v189
	v_add_f32_e32 v36, v190, v117
	v_add_f32_e32 v37, v191, v133
	v_mul_f32_e32 v188, v34, v37
	v_mul_f32_e32 v189, v35, v37
	v_fma_f32 v190, v32, v36, -v188
	v_fma_f32 v191, v33, v36, v189
	v_add_f32_e32 v36, v190, v118
	v_add_f32_e32 v37, v191, v134
	v_mul_f32_e32 v188, v34, v37
	v_mul_f32_e32 v189, v35, v37
	v_fma_f32 v190, v32, v36, -v188
	v_fma_f32 v191, v33, v36, v189
	v_add_f32_e32 v36, v190, v119
	v_add_f32_e32 v37, v191, v135
	v_mul_f32_e32 v188, v34, v37
	v_mul_f32_e32 v189, v35, v37
	v_fma_f32 v190, v32, v36, -v188
	v_fma_f32 v191, v33, v36, v189
	v_add_f32_e32 v36, v190, v154
	v_add_f32_e32 v37, v191, v170
	v_mul_f32_e32 v188, v34, v37
	v_mul_f32_e32 v189, v35, v37
	v_fma_f32 v190, v32, v36, -v188
	v_fma_f32 v191, v33, v36, v189
	v_add_f32_e32 v36, v190, v155
	v_add_f32_e32 v37, v191, v171
	v_mul_f32_e32 v188, v34, v37
	v_mul_f32_e32 v189, v35, v37
	v_fma_f32 v190, v32, v36, -v188
	v_fma_f32 v191, v33, v36, v189
	v_add_f32_e32 v36, v190, v156
	v_add_f32_e32 v37, v191, v172
	v_mul_f32_e32 v188, v34, v37
	v_mul_f32_e32 v189, v35, v37
	v_fma_f32 v190, v32, v36, -v188
	v_fma_f32 v191, v33, v36, v189
	v_add_f32_e32 v36, v190, v157
	v_add_f32_e32 v37, v191, v173
	v_mul_f32_e32 v188, v34, v37
	v_mul_f32_e32 v189, v35, v37
	v_fma_f32 v190, v32, v36, -v188
	v_fma_f32 v191, v33, v36, v189
	v_add_f32_e32 v36, v190, v120
	v_add_f32_e32 v37, v191, v136
	v_mul_f32_e32 v188, v34, v37
	v_mul_f32_e32 v189, v35, v37
	v_fma_f32 v190, v32, v36, -v188
	v_fma_f32 v191, v33, v36, v189
	v_add_f32_e32 v36, v190, v121
	v_add_f32_e32 v37, v191, v137
	v_mul_f32_e32 v188, v34, v37
	v_mul_f32_e32 v189, v35, v37
	v_fma_f32 v190, v32, v36, -v188
	v_fma_f32 v191, v33, v36, v189
	v_add_f32_e32 v36, v190, v122
	v_add_f32_e32 v37, v191, v138
	v_mul_f32_e32 v188, v34, v37
	v_mul_f32_e32 v189, v35, v37
	v_fma_f32 v190, v32, v36, -v188
	v_fma_f32 v191, v33, v36, v189
	v_add_f32_e32 v36, v190, v123
	v_add_f32_e32 v37, v191, v139
	v_mul_f32_e32 v188, v34, v37
	v_mul_f32_e32 v189, v35, v37
	v_fma_f32 v190, v32, v36, -v188
	v_fma_f32 v191, v33, v36, v189
	v_add_f32_e32 v36, v190, v158
	v_add_f32_e32 v37, v191, v174
	v_mul_f32_e32 v188, v34, v37
	v_mul_f32_e32 v189, v35, v37
	v_fma_f32 v190, v32, v36, -v188
	v_fma_f32 v191, v33, v36, v189
	v_add_f32_e32 v36, v190, v159
	v_add_f32_e32 v37, v191, v175
	v_mul_f32_e32 v188, v34, v37
	v_mul_f32_e32 v189, v35, v37
	v_fma_f32 v190, v32, v36, -v188
	v_fma_f32 v191, v33, v36, v189
	v_add_f32_e32 v36, v190, v160
	v_add_f32_e32 v37, v191, v176
	v_mul_f32_e32 v188, v34, v37
	v_mul_f32_e32 v189, v35, v37
	v_fma_f32 v190, v32, v36, -v188
	v_fma_f32 v191, v33, v36, v189
	v_add_f32_e32 v36, v190, v161
	v_add_f32_e32 v37, v191, v177
	v_mov_b32_e32 v38, v37
	s_lshl_b32 s1, s1, 12
	s_lshl_b32 s0, s0, 5
	s_or_b32 s0, s0, s1
	v_or_b32_e32 v0, s0, v40
	v_lshlrev_b32_e32 v1, 1, v39
	v_readlane_b32 s0, v253, 38
	v_lshl_or_b32 v144, v0, 7, v1
	v_readlane_b32 s1, v253, 39
	v_readlane_b32 s2, v253, 40
	v_readlane_b32 s3, v253, 41
	v_lshl_add_u64 v[0:1], v[144:145], 2, s[0:1]
	v_readlane_b32 s4, v253, 42
	v_readlane_b32 s5, v253, 43
	v_readlane_b32 s6, v253, 44
	v_readlane_b32 s7, v253, 45
	global_store_dwordx2 v[0:1], v[36:37], off

; __device__ __forceinline__ bf f2bf(float f) { return (bf)(pk2(f, 0.f) & 0xFFFFu); }
; __device__ __forceinline__ void s5_pass2(const Params& p, int layer, int task, char* sm) {
;     ...
;       for (int l = 0; l < 32; l++) {
;         S5_STEP(sU + l * 16)
;         sS[l * 136 + lane] = f2bf(sr); sS[l * 136 + 64 + lane] = f2bf(si);
.LBB0_1796:
	v_add_u32_e32 v103, v79, v40
	v_and_b32_e32 v43, 31, v202
	v_lshrrev_b32_e32 v42, 5, v202
	v_lshlrev_b32_e32 v43, 6, v43
	v_lshl_add_u32 v43, v42, 2, v43
	v_add_u32_e32 v43, v79, v43
	ds_read2_b32 v[170:171], v43 offset0:0 offset1:2
	ds_read2_b32 v[172:173], v43 offset0:4 offset1:6
	ds_read2_b32 v[174:175], v43 offset0:8 offset1:10
	ds_read2_b32 v[176:177], v43 offset0:12 offset1:14
	s_setprio 1
	s_waitcnt lgkmcnt(3)
	v_mfma_f32_32x32x2_f32 v[104:119], v170, v52, 0
	v_mfma_f32_32x32x2_f32 v[120:135], v170, v53, 0
	v_mfma_f32_32x32x2_f32 v[152:167], v170, v20, 0
	v_mfma_f32_32x32x2_f32 v[136:151], v170, v21, 0
	v_mfma_f32_32x32x2_f32 v[104:119], v171, v54, v[104:119]
	v_mfma_f32_32x32x2_f32 v[120:135], v171, v55, v[120:135]
	v_mfma_f32_32x32x2_f32 v[152:167], v171, v22, v[152:167]
	v_mfma_f32_32x32x2_f32 v[136:151], v171, v23, v[136:151]
	s_waitcnt lgkmcnt(2)
	v_mfma_f32_32x32x2_f32 v[104:119], v172, v56, v[104:119]
	v_mfma_f32_32x32x2_f32 v[120:135], v172, v57, v[120:135]
	v_mfma_f32_32x32x2_f32 v[152:167], v172, v16, v[152:167]
	v_mfma_f32_32x32x2_f32 v[136:151], v172, v17, v[136:151]
	v_mfma_f32_32x32x2_f32 v[104:119], v173, v58, v[104:119]
	v_mfma_f32_32x32x2_f32 v[120:135], v173, v59, v[120:135]
	v_mfma_f32_32x32x2_f32 v[152:167], v173, v18, v[152:167]
	v_mfma_f32_32x32x2_f32 v[136:151], v173, v19, v[136:151]
	s_waitcnt lgkmcnt(1)
	v_mfma_f32_32x32x2_f32 v[104:119], v174, v60, v[104:119]
	v_mfma_f32_32x32x2_f32 v[120:135], v174, v61, v[120:135]
	v_mfma_f32_32x32x2_f32 v[152:167], v174, v12, v[152:167]
	v_mfma_f32_32x32x2_f32 v[136:151], v174, v13, v[136:151]
	v_mfma_f32_32x32x2_f32 v[104:119], v175, v62, v[104:119]
	v_mfma_f32_32x32x2_f32 v[120:135], v175, v63, v[120:135]
	v_mfma_f32_32x32x2_f32 v[152:167], v175, v14, v[152:167]
	v_mfma_f32_32x32x2_f32 v[136:151], v175, v15, v[136:151]
	s_waitcnt lgkmcnt(0)
	v_mfma_f32_32x32x2_f32 v[104:119], v176, v64, v[104:119]
	v_mfma_f32_32x32x2_f32 v[120:135], v176, v65, v[120:135]
	v_mfma_f32_32x32x2_f32 v[152:167], v176, v8, v[152:167]
	v_mfma_f32_32x32x2_f32 v[136:151], v176, v9, v[136:151]
	v_mfma_f32_32x32x2_f32 v[104:119], v177, v66, v[104:119]
	v_mfma_f32_32x32x2_f32 v[120:135], v177, v67, v[120:135]
	v_mfma_f32_32x32x2_f32 v[152:167], v177, v10, v[152:167]
	v_mfma_f32_32x32x2_f32 v[136:151], v177, v11, v[136:151]
	s_setprio 0
	s_nop 7
	s_nop 7
	s_nop 7
	v_permlane32_swap_b32_e32 v104, v152
	v_permlane32_swap_b32_e32 v120, v136
	v_permlane32_swap_b32_e32 v105, v153
	v_permlane32_swap_b32_e32 v121, v137
	v_permlane32_swap_b32_e32 v106, v154
	v_permlane32_swap_b32_e32 v122, v138
	v_permlane32_swap_b32_e32 v107, v155
	v_permlane32_swap_b32_e32 v123, v139
	v_permlane32_swap_b32_e32 v108, v156
	v_permlane32_swap_b32_e32 v124, v140
	v_permlane32_swap_b32_e32 v109, v157
	v_permlane32_swap_b32_e32 v125, v141
	v_permlane32_swap_b32_e32 v110, v158
	v_permlane32_swap_b32_e32 v126, v142
	v_permlane32_swap_b32_e32 v111, v159
	v_permlane32_swap_b32_e32 v127, v143
	v_permlane32_swap_b32_e32 v112, v160
	v_permlane32_swap_b32_e32 v128, v144
	v_permlane32_swap_b32_e32 v113, v161
	v_permlane32_swap_b32_e32 v129, v145
	v_permlane32_swap_b32_e32 v114, v162
	v_permlane32_swap_b32_e32 v130, v146
	v_permlane32_swap_b32_e32 v115, v163
	v_permlane32_swap_b32_e32 v131, v147
	v_permlane32_swap_b32_e32 v116, v164
	v_permlane32_swap_b32_e32 v132, v148
	v_permlane32_swap_b32_e32 v117, v165
	v_permlane32_swap_b32_e32 v133, v149
	v_permlane32_swap_b32_e32 v118, v166
	v_permlane32_swap_b32_e32 v134, v150
	v_permlane32_swap_b32_e32 v119, v167
	v_permlane32_swap_b32_e32 v135, v151
	s_waitcnt vmcnt(5)
	v_mul_f32_e32 v76, v74, v71
	v_mul_f32_e32 v77, v75, v71
	v_fma_f32 v40, v68, v70, -v76
	v_fma_f32 v41, v69, v70, v77
	v_add_f32_e32 v70, v40, v104
	v_add_f32_e32 v71, v41, v120
	v_mul_f32_e32 v76, v74, v71
	v_mul_f32_e32 v77, v75, v71
	v_cvt_pk_bf16_f32 v42, v70, v71
	v_fma_f32 v40, v68, v70, -v76
	v_fma_f32 v41, v69, v70, v77
	ds_write_b16 v103, v42
	v_add_f32_e32 v70, v40, v105
	v_add_f32_e32 v71, v41, v121
	ds_write_b16_d16_hi v103, v42 offset:128
	v_mul_f32_e32 v76, v74, v71
	v_mul_f32_e32 v77, v75, v71
	v_cvt_pk_bf16_f32 v42, v70, v71
	v_fma_f32 v40, v68, v70, -v76
	v_fma_f32 v41, v69, v70, v77
	ds_write_b16 v103, v42 offset:272
	v_add_f32_e32 v70, v40, v106
	v_add_f32_e32 v71, v41, v122
	ds_write_b16_d16_hi v103, v42 offset:400
	v_mul_f32_e32 v76, v74, v71
	v_mul_f32_e32 v77, v75, v71
	v_cvt_pk_bf16_f32 v42, v70, v71
	v_fma_f32 v40, v68, v70, -v76
	v_fma_f32 v41, v69, v70, v77
	ds_write_b16 v103, v42 offset:544
	v_add_f32_e32 v70, v40, v107
	v_add_f32_e32 v71, v41, v123
	ds_write_b16_d16_hi v103, v42 offset:672
	v_mul_f32_e32 v76, v74, v71
	v_mul_f32_e32 v77, v75, v71
	v_cvt_pk_bf16_f32 v42, v70, v71
	v_fma_f32 v40, v68, v70, -v76
	v_fma_f32 v41, v69, v70, v77
	ds_write_b16 v103, v42 offset:816
	v_add_f32_e32 v70, v40, v152
	v_add_f32_e32 v71, v41, v136
	ds_write_b16_d16_hi v103, v42 offset:944
	v_mul_f32_e32 v76, v74, v71
	v_mul_f32_e32 v77, v75, v71
	v_cvt_pk_bf16_f32 v42, v70, v71
	v_fma_f32 v40, v68, v70, -v76
	v_fma_f32 v41, v69, v70, v77
	ds_write_b16 v103, v42 offset:1088
	v_add_f32_e32 v70, v40, v153
	v_add_f32_e32 v71, v41, v137
	ds_write_b16_d16_hi v103, v42 offset:1216
	v_mul_f32_e32 v76, v74, v71
	v_mul_f32_e32 v77, v75, v71
	v_cvt_pk_bf16_f32 v42, v70, v71
	v_fma_f32 v40, v68, v70, -v76
	v_fma_f32 v41, v69, v70, v77
	ds_write_b16 v103, v42 offset:1360
	v_add_f32_e32 v70, v40, v154
	v_add_f32_e32 v71, v41, v138
	ds_write_b16_d16_hi v103, v42 offset:1488
	v_mul_f32_e32 v76, v74, v71
	v_mul_f32_e32 v77, v75, v71
	v_cvt_pk_bf16_f32 v42, v70, v71
	v_fma_f32 v40, v68, v70, -v76
	v_fma_f32 v41, v69, v70, v77
; __device__ __forceinline__ bf f2bf(float f) { return (bf)(pk2(f, 0.f) & 0xFFFFu); }
; __device__ __forceinline__ void s5_pass2(const Params& p, int layer, int task, char* sm) {
;     ...
;       for (int l = 0; l < 32; l++) {
;         S5_STEP(sU + l * 16)
;         sS[l * 136 + lane] = f2bf(sr); sS[l * 136 + 64 + lane] = f2bf(si);
	ds_write_b16 v103, v42 offset:1632
	v_add_f32_e32 v70, v40, v155
	v_add_f32_e32 v71, v41, v139
	ds_write_b16_d16_hi v103, v42 offset:1760
	v_mul_f32_e32 v76, v74, v71
	v_mul_f32_e32 v77, v75, v71
	v_cvt_pk_bf16_f32 v42, v70, v71
	v_fma_f32 v40, v68, v70, -v76
	v_fma_f32 v41, v69, v70, v77
	ds_write_b16 v103, v42 offset:1904
	v_add_f32_e32 v70, v40, v108
	v_add_f32_e32 v71, v41, v124
	ds_write_b16_d16_hi v103, v42 offset:2032
	v_mul_f32_e32 v76, v74, v71
	v_mul_f32_e32 v77, v75, v71
	v_cvt_pk_bf16_f32 v42, v70, v71
	v_fma_f32 v40, v68, v70, -v76
	v_fma_f32 v41, v69, v70, v77
	ds_write_b16 v103, v42 offset:2176
	v_add_f32_e32 v70, v40, v109
	v_add_f32_e32 v71, v41, v125
	ds_write_b16_d16_hi v103, v42 offset:2304
	v_mul_f32_e32 v76, v74, v71
	v_mul_f32_e32 v77, v75, v71
	v_cvt_pk_bf16_f32 v42, v70, v71
	v_fma_f32 v40, v68, v70, -v76
	v_fma_f32 v41, v69, v70, v77
	ds_write_b16 v103, v42 offset:2448
	v_add_f32_e32 v70, v40, v110
	v_add_f32_e32 v71, v41, v126
	ds_write_b16_d16_hi v103, v42 offset:2576
	v_mul_f32_e32 v76, v74, v71
	v_mul_f32_e32 v77, v75, v71
	v_cvt_pk_bf16_f32 v42, v70, v71
	v_fma_f32 v40, v68, v70, -v76
	v_fma_f32 v41, v69, v70, v77
	ds_write_b16 v103, v42 offset:2720
	v_add_f32_e32 v70, v40, v111
	v_add_f32_e32 v71, v41, v127
	ds_write_b16_d16_hi v103, v42 offset:2848
	v_mul_f32_e32 v76, v74, v71
	v_mul_f32_e32 v77, v75, v71
	v_cvt_pk_bf16_f32 v42, v70, v71
	v_fma_f32 v40, v68, v70, -v76
	v_fma_f32 v41, v69, v70, v77
	ds_write_b16 v103, v42 offset:2992
	v_add_f32_e32 v70, v40, v156
	v_add_f32_e32 v71, v41, v140
	ds_write_b16_d16_hi v103, v42 offset:3120
	v_mul_f32_e32 v76, v74, v71
	v_mul_f32_e32 v77, v75, v71
	v_cvt_pk_bf16_f32 v42, v70, v71
	v_fma_f32 v40, v68, v70, -v76
	v_fma_f32 v41, v69, v70, v77
	ds_write_b16 v103, v42 offset:3264
	v_add_f32_e32 v70, v40, v157
	v_add_f32_e32 v71, v41, v141
	ds_write_b16_d16_hi v103, v42 offset:3392
	v_mul_f32_e32 v76, v74, v71
	v_mul_f32_e32 v77, v75, v71
	v_cvt_pk_bf16_f32 v42, v70, v71
	v_fma_f32 v40, v68, v70, -v76
	v_fma_f32 v41, v69, v70, v77
	ds_write_b16 v103, v42 offset:3536
	v_add_f32_e32 v70, v40, v158
	v_add_f32_e32 v71, v41, v142
	ds_write_b16_d16_hi v103, v42 offset:3664
	v_mul_f32_e32 v76, v74, v71
	v_mul_f32_e32 v77, v75, v71
	v_cvt_pk_bf16_f32 v42, v70, v71
	v_fma_f32 v40, v68, v70, -v76
	v_fma_f32 v41, v69, v70, v77
	ds_write_b16 v103, v42 offset:3808
	v_add_f32_e32 v70, v40, v159
	v_add_f32_e32 v71, v41, v143
	ds_write_b16_d16_hi v103, v42 offset:3936
	v_mul_f32_e32 v76, v74, v71
	v_mul_f32_e32 v77, v75, v71
	v_cvt_pk_bf16_f32 v42, v70, v71
	v_fma_f32 v40, v68, v70, -v76
	v_fma_f32 v41, v69, v70, v77
	ds_write_b16 v103, v42 offset:4080
	v_add_f32_e32 v70, v40, v112
	v_add_f32_e32 v71, v41, v128
	ds_write_b16_d16_hi v103, v42 offset:4208
	v_mul_f32_e32 v76, v74, v71
	v_mul_f32_e32 v77, v75, v71
	v_cvt_pk_bf16_f32 v42, v70, v71
	v_fma_f32 v40, v68, v70, -v76
	v_fma_f32 v41, v69, v70, v77
	ds_write_b16 v103, v42 offset:4352
	v_add_f32_e32 v70, v40, v113
	v_add_f32_e32 v71, v41, v129
	ds_write_b16_d16_hi v103, v42 offset:4480
	v_mul_f32_e32 v76, v74, v71
	v_mul_f32_e32 v77, v75, v71
	v_cvt_pk_bf16_f32 v42, v70, v71
	v_fma_f32 v40, v68, v70, -v76
	v_fma_f32 v41, v69, v70, v77
	ds_write_b16 v103, v42 offset:4624
	v_add_f32_e32 v70, v40, v114
	v_add_f32_e32 v71, v41, v130
	ds_write_b16_d16_hi v103, v42 offset:4752
	v_mul_f32_e32 v76, v74, v71
	v_mul_f32_e32 v77, v75, v71
	v_cvt_pk_bf16_f32 v42, v70, v71
	v_fma_f32 v40, v68, v70, -v76
	v_fma_f32 v41, v69, v70, v77
	ds_write_b16 v103, v42 offset:4896
	v_add_f32_e32 v70, v40, v115
	v_add_f32_e32 v71, v41, v131
	ds_write_b16_d16_hi v103, v42 offset:5024
	v_mul_f32_e32 v76, v74, v71
	v_mul_f32_e32 v77, v75, v71
	v_cvt_pk_bf16_f32 v42, v70, v71
	v_fma_f32 v40, v68, v70, -v76
	v_fma_f32 v41, v69, v70, v77
	ds_write_b16 v103, v42 offset:5168
	v_add_f32_e32 v70, v40, v160
	v_add_f32_e32 v71, v41, v144
	ds_write_b16_d16_hi v103, v42 offset:5296
	v_mul_f32_e32 v76, v74, v71
	v_mul_f32_e32 v77, v75, v71
	v_cvt_pk_bf16_f32 v42, v70, v71
	v_fma_f32 v40, v68, v70, -v76
	v_fma_f32 v41, v69, v70, v77
	ds_write_b16 v103, v42 offset:5440
	v_add_f32_e32 v70, v40, v161
	v_add_f32_e32 v71, v41, v145
	ds_write_b16_d16_hi v103, v42 offset:5568
	v_mul_f32_e32 v76, v74, v71
	v_mul_f32_e32 v77, v75, v71
	v_cvt_pk_bf16_f32 v42, v70, v71
	v_fma_f32 v40, v68, v70, -v76
	v_fma_f32 v41, v69, v70, v77
	ds_write_b16 v103, v42 offset:5712
	v_add_f32_e32 v70, v40, v162
	v_add_f32_e32 v71, v41, v146
	ds_write_b16_d16_hi v103, v42 offset:5840
	v_mul_f32_e32 v76, v74, v71
	v_mul_f32_e32 v77, v75, v71
	v_cvt_pk_bf16_f32 v42, v70, v71
	v_fma_f32 v40, v68, v70, -v76
	v_fma_f32 v41, v69, v70, v77
	ds_write_b16 v103, v42 offset:5984
	v_add_f32_e32 v70, v40, v163
	v_add_f32_e32 v71, v41, v147
	ds_write_b16_d16_hi v103, v42 offset:6112
	v_mul_f32_e32 v76, v74, v71
	v_mul_f32_e32 v77, v75, v71
	v_cvt_pk_bf16_f32 v42, v70, v71
	v_fma_f32 v40, v68, v70, -v76
	v_fma_f32 v41, v69, v70, v77
	ds_write_b16 v103, v42 offset:6256
	v_add_f32_e32 v70, v40, v116
	v_add_f32_e32 v71, v41, v132
	ds_write_b16_d16_hi v103, v42 offset:6384
	v_mul_f32_e32 v76, v74, v71
	v_mul_f32_e32 v77, v75, v71
	v_cvt_pk_bf16_f32 v42, v70, v71
	v_fma_f32 v40, v68, v70, -v76
	v_fma_f32 v41, v69, v70, v77
	ds_write_b16 v103, v42 offset:6528
	v_add_f32_e32 v70, v40, v117
	v_add_f32_e32 v71, v41, v133
	ds_write_b16_d16_hi v103, v42 offset:6656
	v_mul_f32_e32 v76, v74, v71
	v_mul_f32_e32 v77, v75, v71
	v_cvt_pk_bf16_f32 v42, v70, v71
	v_fma_f32 v40, v68, v70, -v76
	v_fma_f32 v41, v69, v70, v77
	ds_write_b16 v103, v42 offset:6800
	v_add_f32_e32 v70, v40, v118
	v_add_f32_e32 v71, v41, v134
; __device__ __forceinline__ float ozero() { float z = 0.f; asm volatile("" : "+v"(z)); return z; }
; __device__ __forceinline__ bf f2bf(float f) { return (bf)(pk2(f, 0.f) & 0xFFFFu); }
; __device__ __forceinline__ f32x4 mfma16(bf16x8 a, bf16x8 b, f32x4 c) { return __builtin_amdgcn_mfma_f32_16x16x32_bf16(a, b, c, 0, 0, 0); }
; __device__ __forceinline__ void s5_pass2(const Params& p, int layer, int task, char* sm) {
;     ...
; #pragma unroll
;       for (int mb = 0; mb < 2; mb++) {
;         const float z_ = ozero(); f32x4 acc = {z_, z_, z_, z_};
; #pragma unroll
;         for (int ks = 0; ks < 4; ks++) {
;           bf16x8 af = *(const bf16x8*)(sS + (16 * mb + (lane & 15)) * 136 + ks * 32 + 8 * (lane >> 4));
;           acc = mfma16(af, cf[ks], acc);
;         }
; #pragma unroll
;         for (int r = 0; r < 4; r++) {
;           const int l = 16 * mb + 4 * (lane >> 4) + r;
;           float y = acc[r] + dsk * sU[l * 16 + (lane & 15)];
;           p.YG[(tok0 + sub * 32 + l) * 512 + g * 16 + (lane & 15)] = f2bf(geluf_(y));
;         }
	ds_write_b16_d16_hi v103, v42 offset:6928
	v_mul_f32_e32 v76, v74, v71
	v_mul_f32_e32 v77, v75, v71
	v_cvt_pk_bf16_f32 v42, v70, v71
	v_fma_f32 v40, v68, v70, -v76
	v_fma_f32 v41, v69, v70, v77
	ds_write_b16 v103, v42 offset:7072
	v_add_f32_e32 v70, v40, v119
	v_add_f32_e32 v71, v41, v135
	ds_write_b16_d16_hi v103, v42 offset:7200
	v_mul_f32_e32 v76, v74, v71
	v_mul_f32_e32 v77, v75, v71
	v_cvt_pk_bf16_f32 v42, v70, v71
	v_fma_f32 v40, v68, v70, -v76
	v_fma_f32 v41, v69, v70, v77
	ds_write_b16 v103, v42 offset:7344
	v_add_f32_e32 v70, v40, v164
	v_add_f32_e32 v71, v41, v148
	ds_write_b16_d16_hi v103, v42 offset:7472
	v_mul_f32_e32 v76, v74, v71
	v_mul_f32_e32 v77, v75, v71
	v_cvt_pk_bf16_f32 v42, v70, v71
	v_fma_f32 v40, v68, v70, -v76
	v_fma_f32 v41, v69, v70, v77
	ds_write_b16 v103, v42 offset:7616
	v_add_f32_e32 v70, v40, v165
	v_add_f32_e32 v71, v41, v149
	ds_write_b16_d16_hi v103, v42 offset:7744
	v_mul_f32_e32 v76, v74, v71
	v_mul_f32_e32 v77, v75, v71
	v_cvt_pk_bf16_f32 v42, v70, v71
	v_fma_f32 v40, v68, v70, -v76
	v_fma_f32 v41, v69, v70, v77
	ds_write_b16 v103, v42 offset:7888
	v_add_f32_e32 v70, v40, v166
	v_add_f32_e32 v71, v41, v150
	ds_write_b16_d16_hi v103, v42 offset:8016
	v_mul_f32_e32 v76, v74, v71
	v_mul_f32_e32 v77, v75, v71
	v_cvt_pk_bf16_f32 v42, v70, v71
	v_fma_f32 v40, v68, v70, -v76
	v_fma_f32 v41, v69, v70, v77
	ds_write_b16 v103, v42 offset:8160
	v_add_f32_e32 v70, v40, v167
	v_add_f32_e32 v71, v41, v151
	ds_write_b16_d16_hi v103, v42 offset:8288
	v_cvt_pk_bf16_f32 v42, v70, v71
	ds_write_b16 v103, v42 offset:8432
	ds_write_b16_d16_hi v103, v42 offset:8560
	s_waitcnt lgkmcnt(0)
	v_mov_b32_e32 v145, 0
	v_mov_b32_e32 v40, v145
	ds_read_b128 v[104:107], v100 offset:2048
	ds_read_b32 v76, v83
	v_mov_b32_e32 v41, v40
	v_mov_b32_e32 v42, v40
	v_mov_b32_e32 v43, v40
	s_lshl_b32 s9, s11, 5
	v_mov_b32_e32 v77, s5
	s_cmp_eq_u32 s8, 4
	s_waitcnt vmcnt(4) lgkmcnt(1)
	v_mfma_f32_16x16x32_bf16 v[40:43], v[104:107], v[24:27], v[40:43]
	ds_read_b128 v[104:107], v100 offset:2112
	s_waitcnt vmcnt(3) lgkmcnt(0)
	v_mfma_f32_16x16x32_bf16 v[40:43], v[104:107], v[28:31], v[40:43]
	ds_read_b128 v[104:107], v100 offset:2176
	s_waitcnt vmcnt(2) lgkmcnt(0)
	v_mfma_f32_16x16x32_bf16 v[40:43], v[104:107], v[32:35], v[40:43]
	ds_read_b128 v[104:107], v100 offset:2240
	s_waitcnt vmcnt(1) lgkmcnt(0)
	v_mfma_f32_16x16x32_bf16 v[40:43], v[104:107], v[36:39], v[40:43]
	s_waitcnt vmcnt(0)
	s_nop 6
	v_fma_f32 v40, v102, v76, v40
	v_mul_f32_e32 v76, 0x3d372713, v40
	v_mul_f32_e32 v76, v40, v76
	v_fma_f32 v76, v40, v76, v40
	v_mul_f32_e32 v76, 0x3f4c422a, v76
	v_add_f32_e32 v76, v76, v76
	v_mul_f32_e32 v76, 0x3fb8aa3b, v76
	v_exp_f32_e32 v76, v76
	v_mul_f32_e32 v40, 0.5, v40
	v_add_f32_e32 v76, 1.0, v76
	v_rcp_f32_e32 v76, v76
	s_nop 0
	v_fma_f32 v76, v76, -2.0, 1.0
	v_add_f32_e32 v76, 1.0, v76
	v_mul_f32_e32 v40, v40, v76
	v_or_b32_e32 v76, s9, v82
	v_or_b32_e32 v76, s4, v76
	v_lshlrev_b64 v[104:105], 10, v[76:77]
	v_cvt_pk_bf16_f32 v40, v40, s0
	v_lshl_add_u64 v[104:105], v[72:73], 0, v[104:105]
	global_store_short v[104:105], v40, off
	ds_read_b32 v40, v85
	s_waitcnt lgkmcnt(0)
	v_fma_f32 v40, v102, v40, v41
	v_mul_f32_e32 v41, 0x3d372713, v40
	v_mul_f32_e32 v41, v40, v41
	v_fma_f32 v41, v40, v41, v40
	v_mul_f32_e32 v41, 0x3f4c422a, v41
	v_add_f32_e32 v41, v41, v41
	v_mul_f32_e32 v41, 0x3fb8aa3b, v41
	v_exp_f32_e32 v41, v41
	v_mul_f32_e32 v40, 0.5, v40
	v_add_f32_e32 v41, 1.0, v41
	v_rcp_f32_e32 v41, v41
	s_nop 0
	v_fma_f32 v41, v41, -2.0, 1.0
	v_add_f32_e32 v41, 1.0, v41
	v_mul_f32_e32 v40, v40, v41
	v_cvt_pk_bf16_f32 v103, v40, s0
	v_or_b32_e32 v40, s9, v84
	v_or_b32_e32 v76, s4, v40
	v_lshlrev_b64 v[40:41], 10, v[76:77]
	v_lshl_add_u64 v[40:41], v[72:73], 0, v[40:41]
	global_store_short v[40:41], v103, off
	ds_read_b32 v40, v87
	s_waitcnt lgkmcnt(0)
	v_fma_f32 v40, v102, v40, v42
	v_mul_f32_e32 v41, 0x3d372713, v40
	v_mul_f32_e32 v41, v40, v41
	v_fma_f32 v41, v40, v41, v40
	v_mul_f32_e32 v41, 0x3f4c422a, v41
	v_add_f32_e32 v41, v41, v41
	v_mul_f32_e32 v41, 0x3fb8aa3b, v41
	v_exp_f32_e32 v41, v41
	v_mul_f32_e32 v40, 0.5, v40
	v_add_f32_e32 v41, 1.0, v41
	v_rcp_f32_e32 v41, v41
	s_nop 0
	v_fma_f32 v41, v41, -2.0, 1.0
	v_add_f32_e32 v41, 1.0, v41
	v_mul_f32_e32 v40, v40, v41
	v_cvt_pk_bf16_f32 v42, v40, s0
	v_or_b32_e32 v40, s9, v86
	v_or_b32_e32 v76, s4, v40
	v_lshlrev_b64 v[40:41], 10, v[76:77]
	v_lshl_add_u64 v[40:41], v[72:73], 0, v[40:41]
	global_store_short v[40:41], v42, off
	ds_read_b32 v40, v89
	s_waitcnt lgkmcnt(0)
; __device__ __forceinline__ float ozero() { float z = 0.f; asm volatile("" : "+v"(z)); return z; }
; __device__ __forceinline__ bf f2bf(float f) { return (bf)(pk2(f, 0.f) & 0xFFFFu); }
; __device__ __forceinline__ f32x4 mfma16(bf16x8 a, bf16x8 b, f32x4 c) { return __builtin_amdgcn_mfma_f32_16x16x32_bf16(a, b, c, 0, 0, 0); }
; __device__ __forceinline__ void s5_pass2(const Params& p, int layer, int task, char* sm) {
;     ...
;     for (int sub = 0; sub < 4; sub++) {
;     ...
; #pragma unroll
;       for (int mb = 0; mb < 2; mb++) {
;         const float z_ = ozero(); f32x4 acc = {z_, z_, z_, z_};
; #pragma unroll
;         for (int ks = 0; ks < 4; ks++) {
;           bf16x8 af = *(const bf16x8*)(sS + (16 * mb + (lane & 15)) * 136 + ks * 32 + 8 * (lane >> 4));
;           acc = mfma16(af, cf[ks], acc);
;         }
; #pragma unroll
;         for (int r = 0; r < 4; r++) {
;           const int l = 16 * mb + 4 * (lane >> 4) + r;
;           float y = acc[r] + dsk * sU[l * 16 + (lane & 15)];
;           p.YG[(tok0 + sub * 32 + l) * 512 + g * 16 + (lane & 15)] = f2bf(geluf_(y));
;         }
	v_fmac_f32_e32 v43, v102, v40
	v_mul_f32_e32 v40, 0x3d372713, v43
	v_mul_f32_e32 v40, v43, v40
	v_fma_f32 v40, v43, v40, v43
	v_mul_f32_e32 v40, 0x3f4c422a, v40
	v_add_f32_e32 v40, v40, v40
	v_mul_f32_e32 v40, 0x3fb8aa3b, v40
	v_exp_f32_e32 v40, v40
	v_mul_f32_e32 v41, 0.5, v43
	v_add_f32_e32 v40, 1.0, v40
	v_rcp_f32_e32 v40, v40
	s_nop 0
	v_fma_f32 v40, v40, -2.0, 1.0
	v_add_f32_e32 v40, 1.0, v40
	v_mul_f32_e32 v40, v41, v40
	v_cvt_pk_bf16_f32 v42, v40, s0
	v_or_b32_e32 v40, s9, v88
	v_or_b32_e32 v76, s4, v40
	v_lshlrev_b64 v[40:41], 10, v[76:77]
	v_lshl_add_u64 v[40:41], v[72:73], 0, v[40:41]
	global_store_short v[40:41], v42, off
	v_mov_b32_e32 v40, v145
	ds_read_b128 v[104:107], v100 offset:6400
	ds_read_b32 v76, v91
	v_mov_b32_e32 v41, v40
	v_mov_b32_e32 v42, v40
	v_mov_b32_e32 v43, v40
	s_waitcnt lgkmcnt(1)
	s_nop 0
	v_mfma_f32_16x16x32_bf16 v[40:43], v[104:107], v[24:27], v[40:43]
	ds_read_b128 v[104:107], v100 offset:6464
	s_waitcnt lgkmcnt(0)
	v_mfma_f32_16x16x32_bf16 v[40:43], v[104:107], v[28:31], v[40:43]
	ds_read_b128 v[104:107], v100 offset:6528
	s_waitcnt lgkmcnt(0)
	v_mfma_f32_16x16x32_bf16 v[40:43], v[104:107], v[32:35], v[40:43]
	ds_read_b128 v[104:107], v100 offset:6592
	s_waitcnt lgkmcnt(0)
	v_mfma_f32_16x16x32_bf16 v[40:43], v[104:107], v[36:39], v[40:43]
	s_nop 7
	v_fma_f32 v40, v102, v76, v40
	v_mul_f32_e32 v76, 0x3d372713, v40
	v_mul_f32_e32 v76, v40, v76
	v_fma_f32 v76, v40, v76, v40
	v_mul_f32_e32 v76, 0x3f4c422a, v76
	v_add_f32_e32 v76, v76, v76
	v_mul_f32_e32 v76, 0x3fb8aa3b, v76
	v_exp_f32_e32 v76, v76
	v_mul_f32_e32 v40, 0.5, v40
	v_add_f32_e32 v76, 1.0, v76
	v_rcp_f32_e32 v76, v76
	s_nop 0
	v_fma_f32 v76, v76, -2.0, 1.0
	v_add_f32_e32 v76, 1.0, v76
	v_mul_f32_e32 v40, v40, v76
	v_or_b32_e32 v76, s9, v90
	v_or_b32_e32 v76, s4, v76
	v_lshlrev_b64 v[104:105], 10, v[76:77]
	v_cvt_pk_bf16_f32 v40, v40, s0
	v_lshl_add_u64 v[104:105], v[72:73], 0, v[104:105]
	global_store_short v[104:105], v40, off
	ds_read_b32 v40, v93
	s_waitcnt lgkmcnt(0)
	v_fma_f32 v40, v102, v40, v41
	v_mul_f32_e32 v41, 0x3d372713, v40
	v_mul_f32_e32 v41, v40, v41
	v_fma_f32 v41, v40, v41, v40
	v_mul_f32_e32 v41, 0x3f4c422a, v41
	v_add_f32_e32 v41, v41, v41
	v_mul_f32_e32 v41, 0x3fb8aa3b, v41
	v_exp_f32_e32 v41, v41
	v_mul_f32_e32 v40, 0.5, v40
	v_add_f32_e32 v41, 1.0, v41
	v_rcp_f32_e32 v41, v41
	s_nop 0
	v_fma_f32 v41, v41, -2.0, 1.0
	v_add_f32_e32 v41, 1.0, v41
	v_mul_f32_e32 v40, v40, v41
	v_cvt_pk_bf16_f32 v103, v40, s0
	v_or_b32_e32 v40, s9, v92
	v_or_b32_e32 v76, s4, v40
	v_lshlrev_b64 v[40:41], 10, v[76:77]
	v_lshl_add_u64 v[40:41], v[72:73], 0, v[40:41]
	global_store_short v[40:41], v103, off
	ds_read_b32 v40, v95
	s_waitcnt lgkmcnt(0)
	v_fma_f32 v40, v102, v40, v42
	v_mul_f32_e32 v41, 0x3d372713, v40
	v_mul_f32_e32 v41, v40, v41
	v_fma_f32 v41, v40, v41, v40
	v_mul_f32_e32 v41, 0x3f4c422a, v41
	v_add_f32_e32 v41, v41, v41
	v_mul_f32_e32 v41, 0x3fb8aa3b, v41
	v_exp_f32_e32 v41, v41
	v_mul_f32_e32 v40, 0.5, v40
	v_add_f32_e32 v41, 1.0, v41
	v_rcp_f32_e32 v41, v41
	s_nop 0
	v_fma_f32 v41, v41, -2.0, 1.0
	v_add_f32_e32 v41, 1.0, v41
	v_mul_f32_e32 v40, v40, v41
	v_cvt_pk_bf16_f32 v42, v40, s0
	v_or_b32_e32 v40, s9, v94
	v_or_b32_e32 v76, s4, v40
	v_lshlrev_b64 v[40:41], 10, v[76:77]
	v_lshl_add_u64 v[40:41], v[72:73], 0, v[40:41]
	global_store_short v[40:41], v42, off
	ds_read_b32 v40, v97
	s_waitcnt lgkmcnt(0)
	v_fmac_f32_e32 v43, v102, v40
	v_mul_f32_e32 v40, 0x3d372713, v43
	v_mul_f32_e32 v40, v43, v40
	v_fma_f32 v40, v43, v40, v43
	v_mul_f32_e32 v40, 0x3f4c422a, v40
	v_add_f32_e32 v40, v40, v40
	v_mul_f32_e32 v40, 0x3fb8aa3b, v40
	v_exp_f32_e32 v40, v40
	v_mul_f32_e32 v41, 0.5, v43
	v_add_f32_e32 v40, 1.0, v40
	v_rcp_f32_e32 v40, v40
	s_nop 0
	v_fma_f32 v40, v40, -2.0, 1.0
	v_add_f32_e32 v40, 1.0, v40
	v_mul_f32_e32 v40, v41, v40
	v_cvt_pk_bf16_f32 v42, v40, s0
	v_or_b32_e32 v40, s9, v96
	v_or_b32_e32 v76, s4, v40
	v_lshlrev_b64 v[40:41], 10, v[76:77]
	v_lshl_add_u64 v[40:41], v[72:73], 0, v[40:41]
	global_store_short v[40:41], v42, off
	s_cbranch_scc1 .LBB0_1789
	s_mov_b32 s11, s8
	s_branch .LBB0_1791

; __device__ __forceinline__ bf f2bf(float f) { return (bf)(pk2(f, 0.f) & 0xFFFFu); }
; __device__ __forceinline__ void s5_pass2(const Params& p, int layer, int task, char* sm) {
;     ...
;       for (int l = 0; l < 32; l++) {
;         S5_STEP(sU + l * 16)
;         sS[l * 136 + lane] = f2bf(sr); sS[l * 136 + 64 + lane] = f2bf(si);
.LBB0_2060:
	v_add_u32_e32 v103, v79, v40
	v_and_b32_e32 v43, 31, v202
	v_lshrrev_b32_e32 v42, 5, v202
	v_lshlrev_b32_e32 v43, 6, v43
	v_lshl_add_u32 v43, v42, 2, v43
	v_add_u32_e32 v43, v79, v43
	ds_read2_b32 v[170:171], v43 offset0:0 offset1:2
	ds_read2_b32 v[172:173], v43 offset0:4 offset1:6
	ds_read2_b32 v[174:175], v43 offset0:8 offset1:10
	ds_read2_b32 v[176:177], v43 offset0:12 offset1:14
	s_setprio 1
	s_waitcnt lgkmcnt(3)
	v_mfma_f32_32x32x2_f32 v[104:119], v170, v52, 0
	v_mfma_f32_32x32x2_f32 v[120:135], v170, v53, 0
	v_mfma_f32_32x32x2_f32 v[152:167], v170, v20, 0
	v_mfma_f32_32x32x2_f32 v[136:151], v170, v21, 0
	v_mfma_f32_32x32x2_f32 v[104:119], v171, v54, v[104:119]
	v_mfma_f32_32x32x2_f32 v[120:135], v171, v55, v[120:135]
	v_mfma_f32_32x32x2_f32 v[152:167], v171, v22, v[152:167]
	v_mfma_f32_32x32x2_f32 v[136:151], v171, v23, v[136:151]
	s_waitcnt lgkmcnt(2)
	v_mfma_f32_32x32x2_f32 v[104:119], v172, v56, v[104:119]
	v_mfma_f32_32x32x2_f32 v[120:135], v172, v57, v[120:135]
	v_mfma_f32_32x32x2_f32 v[152:167], v172, v16, v[152:167]
	v_mfma_f32_32x32x2_f32 v[136:151], v172, v17, v[136:151]
	v_mfma_f32_32x32x2_f32 v[104:119], v173, v58, v[104:119]
	v_mfma_f32_32x32x2_f32 v[120:135], v173, v59, v[120:135]
	v_mfma_f32_32x32x2_f32 v[152:167], v173, v18, v[152:167]
	v_mfma_f32_32x32x2_f32 v[136:151], v173, v19, v[136:151]
	s_waitcnt lgkmcnt(1)
	v_mfma_f32_32x32x2_f32 v[104:119], v174, v60, v[104:119]
	v_mfma_f32_32x32x2_f32 v[120:135], v174, v61, v[120:135]
	v_mfma_f32_32x32x2_f32 v[152:167], v174, v12, v[152:167]
	v_mfma_f32_32x32x2_f32 v[136:151], v174, v13, v[136:151]
	v_mfma_f32_32x32x2_f32 v[104:119], v175, v62, v[104:119]
	v_mfma_f32_32x32x2_f32 v[120:135], v175, v63, v[120:135]
	v_mfma_f32_32x32x2_f32 v[152:167], v175, v14, v[152:167]
	v_mfma_f32_32x32x2_f32 v[136:151], v175, v15, v[136:151]
	s_waitcnt lgkmcnt(0)
	v_mfma_f32_32x32x2_f32 v[104:119], v176, v64, v[104:119]
	v_mfma_f32_32x32x2_f32 v[120:135], v176, v65, v[120:135]
	v_mfma_f32_32x32x2_f32 v[152:167], v176, v8, v[152:167]
	v_mfma_f32_32x32x2_f32 v[136:151], v176, v9, v[136:151]
	v_mfma_f32_32x32x2_f32 v[104:119], v177, v66, v[104:119]
	v_mfma_f32_32x32x2_f32 v[120:135], v177, v67, v[120:135]
	v_mfma_f32_32x32x2_f32 v[152:167], v177, v10, v[152:167]
	v_mfma_f32_32x32x2_f32 v[136:151], v177, v11, v[136:151]
	s_setprio 0
	s_nop 7
	s_nop 7
	s_nop 7
	v_permlane32_swap_b32_e32 v104, v152
	v_permlane32_swap_b32_e32 v120, v136
	v_permlane32_swap_b32_e32 v105, v153
	v_permlane32_swap_b32_e32 v121, v137
	v_permlane32_swap_b32_e32 v106, v154
	v_permlane32_swap_b32_e32 v122, v138
	v_permlane32_swap_b32_e32 v107, v155
	v_permlane32_swap_b32_e32 v123, v139
	v_permlane32_swap_b32_e32 v108, v156
	v_permlane32_swap_b32_e32 v124, v140
	v_permlane32_swap_b32_e32 v109, v157
	v_permlane32_swap_b32_e32 v125, v141
	v_permlane32_swap_b32_e32 v110, v158
	v_permlane32_swap_b32_e32 v126, v142
	v_permlane32_swap_b32_e32 v111, v159
	v_permlane32_swap_b32_e32 v127, v143
	v_permlane32_swap_b32_e32 v112, v160
	v_permlane32_swap_b32_e32 v128, v144
	v_permlane32_swap_b32_e32 v113, v161
	v_permlane32_swap_b32_e32 v129, v145
	v_permlane32_swap_b32_e32 v114, v162
	v_permlane32_swap_b32_e32 v130, v146
	v_permlane32_swap_b32_e32 v115, v163
	v_permlane32_swap_b32_e32 v131, v147
	v_permlane32_swap_b32_e32 v116, v164
	v_permlane32_swap_b32_e32 v132, v148
	v_permlane32_swap_b32_e32 v117, v165
	v_permlane32_swap_b32_e32 v133, v149
	v_permlane32_swap_b32_e32 v118, v166
	v_permlane32_swap_b32_e32 v134, v150
	v_permlane32_swap_b32_e32 v119, v167
	v_permlane32_swap_b32_e32 v135, v151
	s_waitcnt vmcnt(5)
	v_mul_f32_e32 v76, v74, v71
	v_mul_f32_e32 v77, v75, v71
	v_fma_f32 v40, v68, v70, -v76
	v_fma_f32 v41, v69, v70, v77
	v_add_f32_e32 v70, v40, v104
	v_add_f32_e32 v71, v41, v120
	v_mul_f32_e32 v76, v74, v71
	v_mul_f32_e32 v77, v75, v71
	v_cvt_pk_bf16_f32 v42, v70, v71
	v_fma_f32 v40, v68, v70, -v76
	v_fma_f32 v41, v69, v70, v77
	ds_write_b16 v103, v42
	v_add_f32_e32 v70, v40, v105
	v_add_f32_e32 v71, v41, v121
	ds_write_b16_d16_hi v103, v42 offset:128
	v_mul_f32_e32 v76, v74, v71
	v_mul_f32_e32 v77, v75, v71
	v_cvt_pk_bf16_f32 v42, v70, v71
	v_fma_f32 v40, v68, v70, -v76
	v_fma_f32 v41, v69, v70, v77
	ds_write_b16 v103, v42 offset:272
	v_add_f32_e32 v70, v40, v106
	v_add_f32_e32 v71, v41, v122
	ds_write_b16_d16_hi v103, v42 offset:400
	v_mul_f32_e32 v76, v74, v71
	v_mul_f32_e32 v77, v75, v71
	v_cvt_pk_bf16_f32 v42, v70, v71
	v_fma_f32 v40, v68, v70, -v76
	v_fma_f32 v41, v69, v70, v77
	ds_write_b16 v103, v42 offset:544
	v_add_f32_e32 v70, v40, v107
	v_add_f32_e32 v71, v41, v123
	ds_write_b16_d16_hi v103, v42 offset:672
	v_mul_f32_e32 v76, v74, v71
	v_mul_f32_e32 v77, v75, v71
	v_cvt_pk_bf16_f32 v42, v70, v71
	v_fma_f32 v40, v68, v70, -v76
	v_fma_f32 v41, v69, v70, v77
	ds_write_b16 v103, v42 offset:816
	v_add_f32_e32 v70, v40, v152
	v_add_f32_e32 v71, v41, v136
	ds_write_b16_d16_hi v103, v42 offset:944
	v_mul_f32_e32 v76, v74, v71
	v_mul_f32_e32 v77, v75, v71
	v_cvt_pk_bf16_f32 v42, v70, v71
	v_fma_f32 v40, v68, v70, -v76
	v_fma_f32 v41, v69, v70, v77
	ds_write_b16 v103, v42 offset:1088
	v_add_f32_e32 v70, v40, v153
	v_add_f32_e32 v71, v41, v137
	ds_write_b16_d16_hi v103, v42 offset:1216
	v_mul_f32_e32 v76, v74, v71
	v_mul_f32_e32 v77, v75, v71
	v_cvt_pk_bf16_f32 v42, v70, v71
	v_fma_f32 v40, v68, v70, -v76
	v_fma_f32 v41, v69, v70, v77
	ds_write_b16 v103, v42 offset:1360
	v_add_f32_e32 v70, v40, v154
	v_add_f32_e32 v71, v41, v138
	ds_write_b16_d16_hi v103, v42 offset:1488
	v_mul_f32_e32 v76, v74, v71
	v_mul_f32_e32 v77, v75, v71
	v_cvt_pk_bf16_f32 v42, v70, v71
	v_fma_f32 v40, v68, v70, -v76
	v_fma_f32 v41, v69, v70, v77
; __device__ __forceinline__ bf f2bf(float f) { return (bf)(pk2(f, 0.f) & 0xFFFFu); }
; __device__ __forceinline__ void s5_pass2(const Params& p, int layer, int task, char* sm) {
;     ...
;       for (int l = 0; l < 32; l++) {
;         S5_STEP(sU + l * 16)
;         sS[l * 136 + lane] = f2bf(sr); sS[l * 136 + 64 + lane] = f2bf(si);
	ds_write_b16 v103, v42 offset:1632
	v_add_f32_e32 v70, v40, v155
	v_add_f32_e32 v71, v41, v139
	ds_write_b16_d16_hi v103, v42 offset:1760
	v_mul_f32_e32 v76, v74, v71
	v_mul_f32_e32 v77, v75, v71
	v_cvt_pk_bf16_f32 v42, v70, v71
	v_fma_f32 v40, v68, v70, -v76
	v_fma_f32 v41, v69, v70, v77
	ds_write_b16 v103, v42 offset:1904
	v_add_f32_e32 v70, v40, v108
	v_add_f32_e32 v71, v41, v124
	ds_write_b16_d16_hi v103, v42 offset:2032
	v_mul_f32_e32 v76, v74, v71
	v_mul_f32_e32 v77, v75, v71
	v_cvt_pk_bf16_f32 v42, v70, v71
	v_fma_f32 v40, v68, v70, -v76
	v_fma_f32 v41, v69, v70, v77
	ds_write_b16 v103, v42 offset:2176
	v_add_f32_e32 v70, v40, v109
	v_add_f32_e32 v71, v41, v125
	ds_write_b16_d16_hi v103, v42 offset:2304
	v_mul_f32_e32 v76, v74, v71
	v_mul_f32_e32 v77, v75, v71
	v_cvt_pk_bf16_f32 v42, v70, v71
	v_fma_f32 v40, v68, v70, -v76
	v_fma_f32 v41, v69, v70, v77
	ds_write_b16 v103, v42 offset:2448
	v_add_f32_e32 v70, v40, v110
	v_add_f32_e32 v71, v41, v126
	ds_write_b16_d16_hi v103, v42 offset:2576
	v_mul_f32_e32 v76, v74, v71
	v_mul_f32_e32 v77, v75, v71
	v_cvt_pk_bf16_f32 v42, v70, v71
	v_fma_f32 v40, v68, v70, -v76
	v_fma_f32 v41, v69, v70, v77
	ds_write_b16 v103, v42 offset:2720
	v_add_f32_e32 v70, v40, v111
	v_add_f32_e32 v71, v41, v127
	ds_write_b16_d16_hi v103, v42 offset:2848
	v_mul_f32_e32 v76, v74, v71
	v_mul_f32_e32 v77, v75, v71
	v_cvt_pk_bf16_f32 v42, v70, v71
	v_fma_f32 v40, v68, v70, -v76
	v_fma_f32 v41, v69, v70, v77
	ds_write_b16 v103, v42 offset:2992
	v_add_f32_e32 v70, v40, v156
	v_add_f32_e32 v71, v41, v140
	ds_write_b16_d16_hi v103, v42 offset:3120
	v_mul_f32_e32 v76, v74, v71
	v_mul_f32_e32 v77, v75, v71
	v_cvt_pk_bf16_f32 v42, v70, v71
	v_fma_f32 v40, v68, v70, -v76
	v_fma_f32 v41, v69, v70, v77
	ds_write_b16 v103, v42 offset:3264
	v_add_f32_e32 v70, v40, v157
	v_add_f32_e32 v71, v41, v141
	ds_write_b16_d16_hi v103, v42 offset:3392
	v_mul_f32_e32 v76, v74, v71
	v_mul_f32_e32 v77, v75, v71
	v_cvt_pk_bf16_f32 v42, v70, v71
	v_fma_f32 v40, v68, v70, -v76
	v_fma_f32 v41, v69, v70, v77
	ds_write_b16 v103, v42 offset:3536
	v_add_f32_e32 v70, v40, v158
	v_add_f32_e32 v71, v41, v142
	ds_write_b16_d16_hi v103, v42 offset:3664
	v_mul_f32_e32 v76, v74, v71
	v_mul_f32_e32 v77, v75, v71
	v_cvt_pk_bf16_f32 v42, v70, v71
	v_fma_f32 v40, v68, v70, -v76
	v_fma_f32 v41, v69, v70, v77
	ds_write_b16 v103, v42 offset:3808
	v_add_f32_e32 v70, v40, v159
	v_add_f32_e32 v71, v41, v143
	ds_write_b16_d16_hi v103, v42 offset:3936
	v_mul_f32_e32 v76, v74, v71
	v_mul_f32_e32 v77, v75, v71
	v_cvt_pk_bf16_f32 v42, v70, v71
	v_fma_f32 v40, v68, v70, -v76
	v_fma_f32 v41, v69, v70, v77
	ds_write_b16 v103, v42 offset:4080
	v_add_f32_e32 v70, v40, v112
	v_add_f32_e32 v71, v41, v128
	ds_write_b16_d16_hi v103, v42 offset:4208
	v_mul_f32_e32 v76, v74, v71
	v_mul_f32_e32 v77, v75, v71
	v_cvt_pk_bf16_f32 v42, v70, v71
	v_fma_f32 v40, v68, v70, -v76
	v_fma_f32 v41, v69, v70, v77
	ds_write_b16 v103, v42 offset:4352
	v_add_f32_e32 v70, v40, v113
	v_add_f32_e32 v71, v41, v129
	ds_write_b16_d16_hi v103, v42 offset:4480
	v_mul_f32_e32 v76, v74, v71
	v_mul_f32_e32 v77, v75, v71
	v_cvt_pk_bf16_f32 v42, v70, v71
	v_fma_f32 v40, v68, v70, -v76
	v_fma_f32 v41, v69, v70, v77
	ds_write_b16 v103, v42 offset:4624
	v_add_f32_e32 v70, v40, v114
	v_add_f32_e32 v71, v41, v130
	ds_write_b16_d16_hi v103, v42 offset:4752
	v_mul_f32_e32 v76, v74, v71
	v_mul_f32_e32 v77, v75, v71
	v_cvt_pk_bf16_f32 v42, v70, v71
	v_fma_f32 v40, v68, v70, -v76
	v_fma_f32 v41, v69, v70, v77
	ds_write_b16 v103, v42 offset:4896
	v_add_f32_e32 v70, v40, v115
	v_add_f32_e32 v71, v41, v131
	ds_write_b16_d16_hi v103, v42 offset:5024
	v_mul_f32_e32 v76, v74, v71
	v_mul_f32_e32 v77, v75, v71
	v_cvt_pk_bf16_f32 v42, v70, v71
	v_fma_f32 v40, v68, v70, -v76
	v_fma_f32 v41, v69, v70, v77
	ds_write_b16 v103, v42 offset:5168
	v_add_f32_e32 v70, v40, v160
	v_add_f32_e32 v71, v41, v144
	ds_write_b16_d16_hi v103, v42 offset:5296
	v_mul_f32_e32 v76, v74, v71
	v_mul_f32_e32 v77, v75, v71
	v_cvt_pk_bf16_f32 v42, v70, v71
	v_fma_f32 v40, v68, v70, -v76
	v_fma_f32 v41, v69, v70, v77
	ds_write_b16 v103, v42 offset:5440
	v_add_f32_e32 v70, v40, v161
	v_add_f32_e32 v71, v41, v145
	ds_write_b16_d16_hi v103, v42 offset:5568
	v_mul_f32_e32 v76, v74, v71
	v_mul_f32_e32 v77, v75, v71
	v_cvt_pk_bf16_f32 v42, v70, v71
	v_fma_f32 v40, v68, v70, -v76
	v_fma_f32 v41, v69, v70, v77
	ds_write_b16 v103, v42 offset:5712
	v_add_f32_e32 v70, v40, v162
	v_add_f32_e32 v71, v41, v146
	ds_write_b16_d16_hi v103, v42 offset:5840
	v_mul_f32_e32 v76, v74, v71
	v_mul_f32_e32 v77, v75, v71
	v_cvt_pk_bf16_f32 v42, v70, v71
	v_fma_f32 v40, v68, v70, -v76
	v_fma_f32 v41, v69, v70, v77
	ds_write_b16 v103, v42 offset:5984
	v_add_f32_e32 v70, v40, v163
	v_add_f32_e32 v71, v41, v147
	ds_write_b16_d16_hi v103, v42 offset:6112
	v_mul_f32_e32 v76, v74, v71
	v_mul_f32_e32 v77, v75, v71
	v_cvt_pk_bf16_f32 v42, v70, v71
	v_fma_f32 v40, v68, v70, -v76
	v_fma_f32 v41, v69, v70, v77
	ds_write_b16 v103, v42 offset:6256
	v_add_f32_e32 v70, v40, v116
	v_add_f32_e32 v71, v41, v132
	ds_write_b16_d16_hi v103, v42 offset:6384
	v_mul_f32_e32 v76, v74, v71
	v_mul_f32_e32 v77, v75, v71
	v_cvt_pk_bf16_f32 v42, v70, v71
	v_fma_f32 v40, v68, v70, -v76
	v_fma_f32 v41, v69, v70, v77
	ds_write_b16 v103, v42 offset:6528
	v_add_f32_e32 v70, v40, v117
	v_add_f32_e32 v71, v41, v133
	ds_write_b16_d16_hi v103, v42 offset:6656
	v_mul_f32_e32 v76, v74, v71
	v_mul_f32_e32 v77, v75, v71
	v_cvt_pk_bf16_f32 v42, v70, v71
	v_fma_f32 v40, v68, v70, -v76
	v_fma_f32 v41, v69, v70, v77
	ds_write_b16 v103, v42 offset:6800
	v_add_f32_e32 v70, v40, v118
	v_add_f32_e32 v71, v41, v134
; __device__ __forceinline__ float ozero() { float z = 0.f; asm volatile("" : "+v"(z)); return z; }
; __device__ __forceinline__ bf f2bf(float f) { return (bf)(pk2(f, 0.f) & 0xFFFFu); }
; __device__ __forceinline__ f32x4 mfma16(bf16x8 a, bf16x8 b, f32x4 c) { return __builtin_amdgcn_mfma_f32_16x16x32_bf16(a, b, c, 0, 0, 0); }
; __device__ __forceinline__ void s5_pass2(const Params& p, int layer, int task, char* sm) {
;     ...
; #pragma unroll
;       for (int mb = 0; mb < 2; mb++) {
;         const float z_ = ozero(); f32x4 acc = {z_, z_, z_, z_};
; #pragma unroll
;         for (int ks = 0; ks < 4; ks++) {
;           bf16x8 af = *(const bf16x8*)(sS + (16 * mb + (lane & 15)) * 136 + ks * 32 + 8 * (lane >> 4));
;           acc = mfma16(af, cf[ks], acc);
;         }
; #pragma unroll
;         for (int r = 0; r < 4; r++) {
;           const int l = 16 * mb + 4 * (lane >> 4) + r;
;           float y = acc[r] + dsk * sU[l * 16 + (lane & 15)];
;           p.YG[(tok0 + sub * 32 + l) * 512 + g * 16 + (lane & 15)] = f2bf(geluf_(y));
;         }
	ds_write_b16_d16_hi v103, v42 offset:6928
	v_mul_f32_e32 v76, v74, v71
	v_mul_f32_e32 v77, v75, v71
	v_cvt_pk_bf16_f32 v42, v70, v71
	v_fma_f32 v40, v68, v70, -v76
	v_fma_f32 v41, v69, v70, v77
	ds_write_b16 v103, v42 offset:7072
	v_add_f32_e32 v70, v40, v119
	v_add_f32_e32 v71, v41, v135
	ds_write_b16_d16_hi v103, v42 offset:7200
	v_mul_f32_e32 v76, v74, v71
	v_mul_f32_e32 v77, v75, v71
	v_cvt_pk_bf16_f32 v42, v70, v71
	v_fma_f32 v40, v68, v70, -v76
	v_fma_f32 v41, v69, v70, v77
	ds_write_b16 v103, v42 offset:7344
	v_add_f32_e32 v70, v40, v164
	v_add_f32_e32 v71, v41, v148
	ds_write_b16_d16_hi v103, v42 offset:7472
	v_mul_f32_e32 v76, v74, v71
	v_mul_f32_e32 v77, v75, v71
	v_cvt_pk_bf16_f32 v42, v70, v71
	v_fma_f32 v40, v68, v70, -v76
	v_fma_f32 v41, v69, v70, v77
	ds_write_b16 v103, v42 offset:7616
	v_add_f32_e32 v70, v40, v165
	v_add_f32_e32 v71, v41, v149
	ds_write_b16_d16_hi v103, v42 offset:7744
	v_mul_f32_e32 v76, v74, v71
	v_mul_f32_e32 v77, v75, v71
	v_cvt_pk_bf16_f32 v42, v70, v71
	v_fma_f32 v40, v68, v70, -v76
	v_fma_f32 v41, v69, v70, v77
	ds_write_b16 v103, v42 offset:7888
	v_add_f32_e32 v70, v40, v166
	v_add_f32_e32 v71, v41, v150
	ds_write_b16_d16_hi v103, v42 offset:8016
	v_mul_f32_e32 v76, v74, v71
	v_mul_f32_e32 v77, v75, v71
	v_cvt_pk_bf16_f32 v42, v70, v71
	v_fma_f32 v40, v68, v70, -v76
	v_fma_f32 v41, v69, v70, v77
	ds_write_b16 v103, v42 offset:8160
	v_add_f32_e32 v70, v40, v167
	v_add_f32_e32 v71, v41, v151
	ds_write_b16_d16_hi v103, v42 offset:8288
	v_cvt_pk_bf16_f32 v42, v70, v71
	ds_write_b16 v103, v42 offset:8432
	ds_write_b16_d16_hi v103, v42 offset:8560
	s_waitcnt lgkmcnt(0)
	v_mov_b32_e32 v145, 0
	v_mov_b32_e32 v40, v145
	ds_read_b128 v[104:107], v100 offset:2048
	ds_read_b32 v76, v83
	v_mov_b32_e32 v41, v40
	v_mov_b32_e32 v42, v40
	v_mov_b32_e32 v43, v40
	s_lshl_b32 s9, s12, 5
	v_mov_b32_e32 v77, s5
	s_cmp_eq_u32 s8, 4
	s_waitcnt vmcnt(4) lgkmcnt(1)
	v_mfma_f32_16x16x32_bf16 v[40:43], v[104:107], v[24:27], v[40:43]
	ds_read_b128 v[104:107], v100 offset:2112
	s_waitcnt vmcnt(3) lgkmcnt(0)
	v_mfma_f32_16x16x32_bf16 v[40:43], v[104:107], v[28:31], v[40:43]
	ds_read_b128 v[104:107], v100 offset:2176
	s_waitcnt vmcnt(2) lgkmcnt(0)
	v_mfma_f32_16x16x32_bf16 v[40:43], v[104:107], v[32:35], v[40:43]
	ds_read_b128 v[104:107], v100 offset:2240
	s_waitcnt vmcnt(1) lgkmcnt(0)
	v_mfma_f32_16x16x32_bf16 v[40:43], v[104:107], v[36:39], v[40:43]
	s_waitcnt vmcnt(0)
	s_nop 6
	v_fma_f32 v40, v102, v76, v40
	v_mul_f32_e32 v76, 0x3d372713, v40
	v_mul_f32_e32 v76, v40, v76
	v_fma_f32 v76, v40, v76, v40
	v_mul_f32_e32 v76, 0x3f4c422a, v76
	v_add_f32_e32 v76, v76, v76
	v_mul_f32_e32 v76, 0x3fb8aa3b, v76
	v_exp_f32_e32 v76, v76
	v_mul_f32_e32 v40, 0.5, v40
	v_add_f32_e32 v76, 1.0, v76
	v_rcp_f32_e32 v76, v76
	s_nop 0
	v_fma_f32 v76, v76, -2.0, 1.0
	v_add_f32_e32 v76, 1.0, v76
	v_mul_f32_e32 v40, v40, v76
	v_or_b32_e32 v76, s9, v82
	v_or_b32_e32 v76, s4, v76
	v_lshlrev_b64 v[104:105], 10, v[76:77]
	v_cvt_pk_bf16_f32 v40, v40, s0
	v_lshl_add_u64 v[104:105], v[72:73], 0, v[104:105]
	global_store_short v[104:105], v40, off
	ds_read_b32 v40, v85
	s_waitcnt lgkmcnt(0)
	v_fma_f32 v40, v102, v40, v41
	v_mul_f32_e32 v41, 0x3d372713, v40
	v_mul_f32_e32 v41, v40, v41
	v_fma_f32 v41, v40, v41, v40
	v_mul_f32_e32 v41, 0x3f4c422a, v41
	v_add_f32_e32 v41, v41, v41
	v_mul_f32_e32 v41, 0x3fb8aa3b, v41
	v_exp_f32_e32 v41, v41
	v_mul_f32_e32 v40, 0.5, v40
	v_add_f32_e32 v41, 1.0, v41
	v_rcp_f32_e32 v41, v41
	s_nop 0
	v_fma_f32 v41, v41, -2.0, 1.0
	v_add_f32_e32 v41, 1.0, v41
	v_mul_f32_e32 v40, v40, v41
	v_cvt_pk_bf16_f32 v103, v40, s0
	v_or_b32_e32 v40, s9, v84
	v_or_b32_e32 v76, s4, v40
	v_lshlrev_b64 v[40:41], 10, v[76:77]
	v_lshl_add_u64 v[40:41], v[72:73], 0, v[40:41]
	global_store_short v[40:41], v103, off
	ds_read_b32 v40, v87
	s_waitcnt lgkmcnt(0)
	v_fma_f32 v40, v102, v40, v42
	v_mul_f32_e32 v41, 0x3d372713, v40
	v_mul_f32_e32 v41, v40, v41
	v_fma_f32 v41, v40, v41, v40
	v_mul_f32_e32 v41, 0x3f4c422a, v41
	v_add_f32_e32 v41, v41, v41
	v_mul_f32_e32 v41, 0x3fb8aa3b, v41
	v_exp_f32_e32 v41, v41
	v_mul_f32_e32 v40, 0.5, v40
	v_add_f32_e32 v41, 1.0, v41
	v_rcp_f32_e32 v41, v41
	s_nop 0
	v_fma_f32 v41, v41, -2.0, 1.0
	v_add_f32_e32 v41, 1.0, v41
	v_mul_f32_e32 v40, v40, v41
	v_cvt_pk_bf16_f32 v42, v40, s0
	v_or_b32_e32 v40, s9, v86
	v_or_b32_e32 v76, s4, v40
	v_lshlrev_b64 v[40:41], 10, v[76:77]
	v_lshl_add_u64 v[40:41], v[72:73], 0, v[40:41]
	global_store_short v[40:41], v42, off
	ds_read_b32 v40, v89
	s_waitcnt lgkmcnt(0)
; __device__ __forceinline__ float ozero() { float z = 0.f; asm volatile("" : "+v"(z)); return z; }
; __device__ __forceinline__ bf f2bf(float f) { return (bf)(pk2(f, 0.f) & 0xFFFFu); }
; __device__ __forceinline__ f32x4 mfma16(bf16x8 a, bf16x8 b, f32x4 c) { return __builtin_amdgcn_mfma_f32_16x16x32_bf16(a, b, c, 0, 0, 0); }
; __device__ __forceinline__ void s5_pass2(const Params& p, int layer, int task, char* sm) {
;     ...
;     for (int sub = 0; sub < 4; sub++) {
;     ...
; #pragma unroll
;       for (int mb = 0; mb < 2; mb++) {
;         const float z_ = ozero(); f32x4 acc = {z_, z_, z_, z_};
; #pragma unroll
;         for (int ks = 0; ks < 4; ks++) {
;           bf16x8 af = *(const bf16x8*)(sS + (16 * mb + (lane & 15)) * 136 + ks * 32 + 8 * (lane >> 4));
;           acc = mfma16(af, cf[ks], acc);
;         }
; #pragma unroll
;         for (int r = 0; r < 4; r++) {
;           const int l = 16 * mb + 4 * (lane >> 4) + r;
;           float y = acc[r] + dsk * sU[l * 16 + (lane & 15)];
;           p.YG[(tok0 + sub * 32 + l) * 512 + g * 16 + (lane & 15)] = f2bf(geluf_(y));
;         }
	v_fmac_f32_e32 v43, v102, v40
	v_mul_f32_e32 v40, 0x3d372713, v43
	v_mul_f32_e32 v40, v43, v40
	v_fma_f32 v40, v43, v40, v43
	v_mul_f32_e32 v40, 0x3f4c422a, v40
	v_add_f32_e32 v40, v40, v40
	v_mul_f32_e32 v40, 0x3fb8aa3b, v40
	v_exp_f32_e32 v40, v40
	v_mul_f32_e32 v41, 0.5, v43
	v_add_f32_e32 v40, 1.0, v40
	v_rcp_f32_e32 v40, v40
	s_nop 0
	v_fma_f32 v40, v40, -2.0, 1.0
	v_add_f32_e32 v40, 1.0, v40
	v_mul_f32_e32 v40, v41, v40
	v_cvt_pk_bf16_f32 v42, v40, s0
	v_or_b32_e32 v40, s9, v88
	v_or_b32_e32 v76, s4, v40
	v_lshlrev_b64 v[40:41], 10, v[76:77]
	v_lshl_add_u64 v[40:41], v[72:73], 0, v[40:41]
	global_store_short v[40:41], v42, off
	v_mov_b32_e32 v40, v145
	ds_read_b128 v[104:107], v100 offset:6400
	ds_read_b32 v76, v91
	v_mov_b32_e32 v41, v40
	v_mov_b32_e32 v42, v40
	v_mov_b32_e32 v43, v40
	s_waitcnt lgkmcnt(1)
	s_nop 0
	v_mfma_f32_16x16x32_bf16 v[40:43], v[104:107], v[24:27], v[40:43]
	ds_read_b128 v[104:107], v100 offset:6464
	s_waitcnt lgkmcnt(0)
	v_mfma_f32_16x16x32_bf16 v[40:43], v[104:107], v[28:31], v[40:43]
	ds_read_b128 v[104:107], v100 offset:6528
	s_waitcnt lgkmcnt(0)
	v_mfma_f32_16x16x32_bf16 v[40:43], v[104:107], v[32:35], v[40:43]
	ds_read_b128 v[104:107], v100 offset:6592
	s_waitcnt lgkmcnt(0)
	v_mfma_f32_16x16x32_bf16 v[40:43], v[104:107], v[36:39], v[40:43]
	s_nop 7
	v_fma_f32 v40, v102, v76, v40
	v_mul_f32_e32 v76, 0x3d372713, v40
	v_mul_f32_e32 v76, v40, v76
	v_fma_f32 v76, v40, v76, v40
	v_mul_f32_e32 v76, 0x3f4c422a, v76
	v_add_f32_e32 v76, v76, v76
	v_mul_f32_e32 v76, 0x3fb8aa3b, v76
	v_exp_f32_e32 v76, v76
	v_mul_f32_e32 v40, 0.5, v40
	v_add_f32_e32 v76, 1.0, v76
	v_rcp_f32_e32 v76, v76
	s_nop 0
	v_fma_f32 v76, v76, -2.0, 1.0
	v_add_f32_e32 v76, 1.0, v76
	v_mul_f32_e32 v40, v40, v76
	v_or_b32_e32 v76, s9, v90
	v_or_b32_e32 v76, s4, v76
	v_lshlrev_b64 v[104:105], 10, v[76:77]
	v_cvt_pk_bf16_f32 v40, v40, s0
	v_lshl_add_u64 v[104:105], v[72:73], 0, v[104:105]
	global_store_short v[104:105], v40, off
	ds_read_b32 v40, v93
	s_waitcnt lgkmcnt(0)
	v_fma_f32 v40, v102, v40, v41
	v_mul_f32_e32 v41, 0x3d372713, v40
	v_mul_f32_e32 v41, v40, v41
	v_fma_f32 v41, v40, v41, v40
	v_mul_f32_e32 v41, 0x3f4c422a, v41
	v_add_f32_e32 v41, v41, v41
	v_mul_f32_e32 v41, 0x3fb8aa3b, v41
	v_exp_f32_e32 v41, v41
	v_mul_f32_e32 v40, 0.5, v40
	v_add_f32_e32 v41, 1.0, v41
	v_rcp_f32_e32 v41, v41
	s_nop 0
	v_fma_f32 v41, v41, -2.0, 1.0
	v_add_f32_e32 v41, 1.0, v41
	v_mul_f32_e32 v40, v40, v41
	v_cvt_pk_bf16_f32 v103, v40, s0
	v_or_b32_e32 v40, s9, v92
	v_or_b32_e32 v76, s4, v40
	v_lshlrev_b64 v[40:41], 10, v[76:77]
	v_lshl_add_u64 v[40:41], v[72:73], 0, v[40:41]
	global_store_short v[40:41], v103, off
	ds_read_b32 v40, v95
	s_waitcnt lgkmcnt(0)
	v_fma_f32 v40, v102, v40, v42
	v_mul_f32_e32 v41, 0x3d372713, v40
	v_mul_f32_e32 v41, v40, v41
	v_fma_f32 v41, v40, v41, v40
	v_mul_f32_e32 v41, 0x3f4c422a, v41
	v_add_f32_e32 v41, v41, v41
	v_mul_f32_e32 v41, 0x3fb8aa3b, v41
	v_exp_f32_e32 v41, v41
	v_mul_f32_e32 v40, 0.5, v40
	v_add_f32_e32 v41, 1.0, v41
	v_rcp_f32_e32 v41, v41
	s_nop 0
	v_fma_f32 v41, v41, -2.0, 1.0
	v_add_f32_e32 v41, 1.0, v41
	v_mul_f32_e32 v40, v40, v41
	v_cvt_pk_bf16_f32 v42, v40, s0
	v_or_b32_e32 v40, s9, v94
	v_or_b32_e32 v76, s4, v40
	v_lshlrev_b64 v[40:41], 10, v[76:77]
	v_lshl_add_u64 v[40:41], v[72:73], 0, v[40:41]
	global_store_short v[40:41], v42, off
	ds_read_b32 v40, v97
	s_waitcnt lgkmcnt(0)
	v_fmac_f32_e32 v43, v102, v40
	v_mul_f32_e32 v40, 0x3d372713, v43
	v_mul_f32_e32 v40, v43, v40
	v_fma_f32 v40, v43, v40, v43
	v_mul_f32_e32 v40, 0x3f4c422a, v40
	v_add_f32_e32 v40, v40, v40
	v_mul_f32_e32 v40, 0x3fb8aa3b, v40
	v_exp_f32_e32 v40, v40
	v_mul_f32_e32 v41, 0.5, v43
	v_add_f32_e32 v40, 1.0, v40
	v_rcp_f32_e32 v40, v40
	s_nop 0
	v_fma_f32 v40, v40, -2.0, 1.0
	v_add_f32_e32 v40, 1.0, v40
	v_mul_f32_e32 v40, v41, v40
	v_cvt_pk_bf16_f32 v42, v40, s0
	v_or_b32_e32 v40, s9, v96
	v_or_b32_e32 v76, s4, v40
	v_lshlrev_b64 v[40:41], 10, v[76:77]
	v_lshl_add_u64 v[40:41], v[72:73], 0, v[40:41]
	global_store_short v[40:41], v42, off
	s_cbranch_scc1 .LBB0_2053
	s_mov_b32 s12, s8
	s_branch .LBB0_2055
